# combined: norm ctx-row slab sum batched loads; rwkv scan loader waves double-buffered; ssd scan chunk loop with batched LDS reads
# speedup vs baseline: 1.0037x; 1.0037x over previous
.LBB0_908:
	s_or_b64 exec, exec, s[6:7]
	s_and_b64 s[6:7], s[36:37], exec
	s_cselect_b32 s6, 0, 0x1b00000
	s_add_u32 s6, s2, s6
	s_movk_i32 s29, 0x110
	s_movk_i32 s28, 0x90
	s_addc_u32 s7, s3, 0
	s_ashr_i32 s20, s8, 1
	v_mad_u32_u24 v8, v104, s29, 0
	s_movk_i32 s18, 0xfef2
	v_mul_lo_u32 v6, v4, s28
	v_and_b32_e32 v7, 15, v86
	v_mad_i32_i24 v10, v104, s18, v8
	v_lshlrev_b32_e32 v4, 2, v104
	v_readlane_b32 s31, v253, 57
	v_readlane_b32 s33, v253, 58
	s_lshl_b32 s18, s20, 4
	v_ashrrev_i32_e32 v0, 4, v86
	v_add_u32_e32 v107, s31, v4
	v_add_u32_e32 v108, s33, v4
	v_or_b32_e32 v4, s18, v7
	s_and_b32 s21, s8, 1
	v_mul_lo_u32 v5, v4, s29
	v_lshl_add_u32 v89, v0, 2, s18
	s_lshl_b32 s18, s20, 6
	v_add_u32_e32 v112, 0, v5
	s_lshl_b32 s25, s21, 1
	v_lshlrev_b32_e32 v0, 7, v4
	s_add_i32 s26, 0, 0x11800
	s_add_i32 s18, s33, s18
	s_lshl_b32 s27, s9, 2
	v_and_b32_e32 v113, -16, v86
	v_sub_u32_e32 v0, v112, v0
	s_add_u32 s6, s6, s27
	v_add_u32_e32 v91, v0, v113
	s_addc_u32 s7, s7, 0
	v_lshlrev_b32_e32 v0, 2, v7
	s_lshl_b32 s34, s21, 7
	v_add_u32_e32 v114, s26, v113
	v_lshl_add_u64 v[4:5], s[6:7], 0, v[0:1]
	s_lshl_b32 s6, s16, 11
	s_or_b32 s7, s17, 0x2000
	s_add_i32 s26, s26, s34
	s_movk_i32 s16, 0x480
	s_cmp_le_i32 s25, s20
	v_lshlrev_b32_e32 v9, 4, v3
	v_lshl_or_b32 v0, s21, 6, v7
	v_lshl_add_u32 v11, v7, 1, s26
	v_mul_lo_u32 v3, v3, s16
	s_cselect_b64 s[16:17], -1, 0
	v_lshl_or_b32 v7, s21, 5, v7
	s_cmp_lt_i32 s25, s20
	v_lshlrev_b32_e32 v12, 2, v138
	v_or_b32_e32 v13, 1, v89
	v_or_b32_e32 v14, 2, v89
	v_or_b32_e32 v15, 3, v89
	s_cselect_b64 s[20:21], -1, 0
	v_or_b32_e32 v16, 16, v7
	v_lshlrev_b32_e32 v38, 2, v7
	v_lshl_add_u64 v[4:5], v[4:5], 0, s[34:35]
	s_mov_b64 s[26:27], 0x40e00000
	s_lshl_b32 s24, s24, 2
	v_add_u32_e32 v97, 0, v113
	v_add_u32_e32 v110, s33, v12
	v_add_u32_e32 v111, s31, v12
	v_add_u32_e32 v6, 0x2400, v6
	v_mul_u32_u24_e32 v103, 0x110, v7
	v_mul_lo_u32 v12, v89, s28
	v_mul_u32_u24_e32 v0, 0x90, v0
	v_mul_lo_u32 v17, v89, s29
	v_add_u32_e32 v101, s33, v38
	v_add_u32_e32 v102, s31, v38
	v_lshl_add_u32 v38, v7, 1, 0
	v_cmp_le_i32_e64 s[52:53], v7, v89
	v_cmp_le_i32_e64 s[50:51], v7, v13
	v_cmp_le_i32_e64 s[48:49], v7, v14
	v_cmp_le_i32_e64 s[46:47], v7, v15
	v_lshlrev_b32_e32 v39, 2, v16
	v_mul_u32_u24_e32 v7, 0x90, v7
	v_lshl_add_u64 v[70:71], v[4:5], 0, s[26:27]
	v_mul_u32_u24_e32 v4, 0x90, v16
	s_add_u32 s24, s4, s24
	s_mov_b32 s15, 0
	v_lshl_add_u32 v96, v89, 2, s33
	v_lshl_add_u32 v95, v13, 2, s33
	v_lshl_add_u32 v93, v14, 2, s33
	v_lshl_add_u32 v92, v15, 2, s33
	v_mul_u32_u24_e32 v100, 0x110, v16
	v_add_u32_e32 v98, s33, v39
	v_add_u32_e32 v99, s31, v39
	v_cmp_le_i32_e64 s[44:45], v16, v89
	v_cmp_le_i32_e64 s[42:43], v16, v13
	v_cmp_le_i32_e64 s[40:41], v16, v14
	v_cmp_le_i32_e64 s[38:39], v16, v15
	s_addc_u32 s25, s5, 0
	v_sub_u32_e32 v117, 0, v89
	v_sub_u32_e32 v118, 0xffffffc0, v104
	s_lshl_b32 s34, s19, 1
	v_add_u32_e32 v116, v8, v9
	v_add_u32_e32 v109, v10, v3
	v_add_u32_e32 v115, v10, v6
	v_add_u32_e32 v94, v38, v12
	v_add_u32_e32 v90, v97, v7
	v_add_u32_e32 v88, v97, v4
	v_add_u32_e32 v87, v97, v0
	v_add_u32_e32 v0, v11, v17
	s_mov_b32 s19, 0
	s_mov_b32 s26, 0
	v_mov_b32_e32 v3, v2
	v_mov_b32_e32 v4, v2
	v_mov_b32_e32 v5, v2
	v_mov_b32_e32 v6, v2
	v_mov_b32_e32 v7, v2
	v_mov_b32_e32 v8, v2
	v_mov_b32_e32 v9, v2
	v_mov_b32_e32 v10, v2
	v_mov_b32_e32 v11, v2
	v_mov_b32_e32 v12, v2
	v_mov_b32_e32 v13, v2
	v_mov_b32_e32 v14, v2
	v_mov_b32_e32 v15, v2
	v_mov_b32_e32 v16, v2
	v_mov_b32_e32 v17, v2
	s_branch .LBB0_910
.LBB0_910:
	s_waitcnt vmcnt(4)
	ds_write_b128 v116, v[30:33]
	s_waitcnt vmcnt(3)
	ds_write_b128 v116, v[34:37] offset:128
	s_waitcnt vmcnt(2)
	ds_write_b128 v116, v[22:25] offset:17408
	s_waitcnt vmcnt(1)
	ds_write_b128 v116, v[18:21] offset:17536
	s_waitcnt vmcnt(0)
	ds_write_b16 v109, v26 offset:53248
	ds_write_b16_d16_hi v109, v26 offset:53392
	ds_write_b16 v109, v27 offset:53536
	ds_write_b16_d16_hi v109, v27 offset:53680
	ds_write_b16 v109, v28 offset:53824
	ds_write_b16_d16_hi v109, v28 offset:53968
	ds_write_b16 v109, v29 offset:54112
	ds_write_b16_d16_hi v109, v29 offset:54256
	s_and_saveexec_b64 s[4:5], s[54:55]
	s_cbranch_execz .LBB0_912
	v_add_f32_dpp v26, v106, v106 row_shr:1 row_mask:0xf bank_mask:0xf bound_ctrl:1
	v_mov_b32_e32 v27, v1
	s_nop 0
	v_add_f32_dpp v26, v26, v26 row_shr:2 row_mask:0xf bank_mask:0xf bound_ctrl:1
	s_nop 1
	v_add_f32_dpp v26, v26, v26 row_shr:4 row_mask:0xf bank_mask:0xf bound_ctrl:1
	s_nop 1
	v_add_f32_dpp v26, v26, v26 row_shr:8 row_mask:0xf bank_mask:0xf bound_ctrl:1
	s_nop 1
	v_mov_b32_dpp v27, v26 row_bcast:15 row_mask:0xa bank_mask:0xf
	v_add_f32_e32 v26, v26, v27
	v_mov_b32_e32 v27, v1
	s_nop 1
	v_mov_b32_dpp v27, v26 row_bcast:31 row_mask:0xc bank_mask:0xf
	v_add_f32_e32 v26, v26, v27
	ds_write_b32 v110, v26
	ds_write_b32 v111, v105
.LBB0_912:
	s_or_b64 exec, exec, s[4:5]
	v_readlane_b32 s4, v253, 59
	s_waitcnt lgkmcnt(0)
	s_barrier
	v_mov_b32_e32 v26, s4
	ds_read_b32 v119, v26
	ds_read_b32 v26, v107
	ds_read_b32 v27, v108
	ds_read_b32 v128, v101
	ds_read_b32 v129, v102
	ds_read_b32 v130, v98
	ds_read_b32 v131, v99
	ds_read_b32 v132, v96
	ds_read_b32 v133, v95
	ds_read_b32 v134, v93
	ds_read_b32 v135, v92
	v_add_u32_e32 v122, v112, v113
	ds_read_b128 v[58:61], v122
	ds_read_b128 v[54:57], v122 offset:64
	ds_read_b128 v[50:53], v122 offset:128
	ds_read_b128 v[46:49], v122 offset:192
	s_cmp_lt_u32 s26, 3
	s_cselect_b64 vcc, -1, 0
	s_and_b64 s[4:5], vcc, exec
	s_movk_i32 s4, 0x8ff
	s_cselect_b32 s4, 0xff, s4
	s_cselect_b32 s5, s7, s6
	s_add_i32 s4, s15, s4
	v_mov_b32_e32 v240, 0
	v_mov_b32_e32 v241, 0
	v_mov_b32_e32 v242, 0
	v_mov_b32_e32 v243, 0
	v_mov_b32_e32 v244, 0
	v_mov_b32_e32 v245, 0
	v_mov_b32_e32 v246, 0
	v_mov_b32_e32 v247, 0
	v_cndmask_b32_e64 v188, 0, 1, s[16:17]
	v_cndmask_b32_e64 v189, 0, 1, s[20:21]
	v_cmp_ne_u32_e64 s[56:57], 1, v188
	v_cmp_ne_u32_e64 s[58:59], 1, v189
	v_add_u32_e32 v42, v97, v103
	v_add_u32_e32 v62, v97, v100
	s_waitcnt lgkmcnt(12)
	v_sub_f32_e32 v27, v119, v27
	v_mul_f32_e32 v27, 0x3fb8aa3b, v27
	v_exp_f32_e32 v27, v27
	s_waitcnt lgkmcnt(4)
	ds_read_b128 v[140:143], v42 offset:17408
	ds_read_b128 v[144:147], v42 offset:17472
	ds_read_b128 v[148:151], v42 offset:17536
	ds_read_b128 v[152:155], v42 offset:17600
	ds_read_b128 v[156:159], v62 offset:17408
	ds_read_b128 v[160:163], v62 offset:17472
	ds_read_b128 v[164:167], v62 offset:17536
	ds_read_b128 v[168:171], v62 offset:17600
	v_mul_f32_e32 v26, v26, v27
	v_lshlrev_b32_e32 v172, 16, v22
	v_mul_f32_e32 v172, v26, v172
	v_cvt_pk_bf16_f32 v172, v172, s0
	v_and_b32_e32 v173, 0xffff0000, v22
	v_mul_f32_e32 v173, v26, v173
	v_cvt_pk_bf16_f32 v173, v173, s0
	v_lshlrev_b32_e32 v174, 16, v23
	v_mul_f32_e32 v174, v26, v174
	v_cvt_pk_bf16_f32 v174, v174, s0
	v_and_b32_e32 v175, 0xffff0000, v23
	v_mul_f32_e32 v175, v26, v175
	v_cvt_pk_bf16_f32 v175, v175, s0
	v_lshlrev_b32_e32 v176, 16, v24
	v_mul_f32_e32 v176, v26, v176
	v_cvt_pk_bf16_f32 v176, v176, s0
	v_and_b32_e32 v177, 0xffff0000, v24
	v_mul_f32_e32 v177, v26, v177
	v_cvt_pk_bf16_f32 v177, v177, s0
	v_lshlrev_b32_e32 v178, 16, v25
	v_mul_f32_e32 v178, v26, v178
	v_cvt_pk_bf16_f32 v178, v178, s0
	v_and_b32_e32 v179, 0xffff0000, v25
	v_mul_f32_e32 v179, v26, v179
	v_cvt_pk_bf16_f32 v179, v179, s0
	v_lshlrev_b32_e32 v180, 16, v18
	v_mul_f32_e32 v180, v26, v180
	v_cvt_pk_bf16_f32 v180, v180, s0
	v_and_b32_e32 v181, 0xffff0000, v18
	v_mul_f32_e32 v181, v26, v181
	v_cvt_pk_bf16_f32 v181, v181, s0
	v_lshlrev_b32_e32 v182, 16, v19
	v_mul_f32_e32 v182, v26, v182
	v_cvt_pk_bf16_f32 v182, v182, s0
	v_and_b32_e32 v183, 0xffff0000, v19
	v_mul_f32_e32 v183, v26, v183
	v_cvt_pk_bf16_f32 v183, v183, s0
	v_lshlrev_b32_e32 v184, 16, v20
	v_mul_f32_e32 v184, v26, v184
	v_cvt_pk_bf16_f32 v184, v184, s0
	v_and_b32_e32 v185, 0xffff0000, v20
	v_mul_f32_e32 v185, v26, v185
	v_cvt_pk_bf16_f32 v185, v185, s0
	v_lshlrev_b32_e32 v186, 16, v21
	v_mul_f32_e32 v186, v26, v186
	v_cvt_pk_bf16_f32 v186, v186, s0
	v_and_b32_e32 v187, 0xffff0000, v21
	v_mul_f32_e32 v187, v26, v187
	v_cvt_pk_bf16_f32 v187, v187, s0
	v_add_u32_e32 v18, s19, v104
	v_add_u32_e32 v19, 64, v18
	v_add_u32_e32 v18, 0xffffff40, v18
	v_cndmask_b32_e32 v18, v18, v19, vcc
	v_add_u32_e32 v19, s4, v118
	v_cndmask_b32_e64 v18, v19, v18, s[36:37]
	v_add_u32_e32 v38, s5, v18
	v_mov_b64_e32 v[18:19], s[12:13]
	s_movk_i32 s4, 0xe00
	v_mad_i64_i32 v[26:27], s[4:5], v38, s4, v[18:19]
	v_lshl_add_u64 v[18:19], v[26:27], 0, s[34:35]
	v_lshl_add_u64 v[18:19], v[18:19], 0, v[72:73]
	s_lshl_b32 s4, s9, 1
	s_mov_b32 s5, s35
	global_load_dwordx4 v[30:33], v[18:19], off offset:2560
	global_load_dwordx4 v[34:37], v[18:19], off offset:2688
	global_load_dwordx4 v[22:25], v[18:19], off offset:1536
	s_nop 0
	global_load_dwordx4 v[18:21], v[18:19], off offset:1664
	v_lshl_add_u64 v[26:27], v[26:27], 0, s[4:5]
	v_lshl_add_u64 v[26:27], v[26:27], 0, v[72:73]
	global_load_dwordx4 v[26:29], v[26:27], off
	s_and_saveexec_b64 s[4:5], s[54:55]
	s_cbranch_execz .Lssd_skip_dt
	v_mov_b64_e32 v[40:41], s[24:25]
	v_mad_i64_i32 v[38:39], s[28:29], v38, s97, v[40:41]
	global_load_dword v105, v[38:39], off
	global_load_dword v106, v[38:39], off offset:96
.Lssd_skip_dt:
	s_or_b64 exec, exec, s[4:5]
	s_waitcnt lgkmcnt(0)
	s_and_b64 s[4:5], s[16:17], exec
	s_cbranch_scc0 .Lssd_g0_skip
	v_mfma_f32_16x16x32_bf16 v[240:243], v[58:61], v[140:143], 0
	v_mfma_f32_16x16x32_bf16 v[240:243], v[54:57], v[144:147], v[240:243]
	v_mfma_f32_16x16x32_bf16 v[240:243], v[50:53], v[148:151], v[240:243]
	v_mfma_f32_16x16x32_bf16 v[240:243], v[46:49], v[152:155], v[240:243]
.Lssd_g0_skip:
	s_and_b64 s[4:5], s[20:21], exec
	s_cbranch_scc0 .Lssd_g1_skip
	v_mfma_f32_16x16x32_bf16 v[244:247], v[58:61], v[156:159], 0
	v_mfma_f32_16x16x32_bf16 v[244:247], v[54:57], v[160:163], v[244:247]
	v_mfma_f32_16x16x32_bf16 v[244:247], v[50:53], v[164:167], v[244:247]
	v_mfma_f32_16x16x32_bf16 v[244:247], v[46:49], v[168:171], v[244:247]
.Lssd_g1_skip:
	ds_write_b16 v109, v172 offset:34816
	ds_write_b16 v109, v173 offset:34960
	ds_write_b16 v109, v174 offset:35104
	ds_write_b16 v109, v175 offset:35248
	ds_write_b16 v109, v176 offset:35392
	ds_write_b16 v109, v177 offset:35536
	ds_write_b16 v109, v178 offset:35680
	ds_write_b16 v109, v179 offset:35824
	ds_write_b16 v115, v180 offset:34816
	ds_write_b16 v109, v181 offset:44176
	ds_write_b16 v109, v182 offset:44320
	ds_write_b16 v109, v183 offset:44464
	ds_write_b16 v109, v184 offset:44608
	ds_write_b16 v109, v185 offset:44752
	ds_write_b16 v109, v186 offset:44896
	ds_write_b16 v109, v187 offset:45040
	v_sub_f32_e32 v188, v132, v128
	v_mul_f32_e32 v188, 0x3fb8aa3b, v188
	v_exp_f32_e32 v188, v188
	v_sub_f32_e32 v189, v133, v128
	v_mul_f32_e32 v189, 0x3fb8aa3b, v189
	v_exp_f32_e32 v189, v189
	v_sub_f32_e32 v190, v134, v128
	v_mul_f32_e32 v190, 0x3fb8aa3b, v190
	v_exp_f32_e32 v190, v190
	v_sub_f32_e32 v191, v135, v128
	v_mul_f32_e32 v191, 0x3fb8aa3b, v191
	v_exp_f32_e32 v191, v191
	v_mul_f32_e32 v188, v240, v188
	v_mul_f32_e32 v188, v129, v188
	v_cvt_pk_bf16_f32 v188, v188, s0
	v_cndmask_b32_e64 v188, 0, v188, s[52:53]
	v_mul_f32_e32 v189, v241, v189
	v_mul_f32_e32 v189, v129, v189
	v_cvt_pk_bf16_f32 v189, v189, s0
	v_cndmask_b32_e64 v189, 0, v189, s[50:51]
	v_mul_f32_e32 v190, v242, v190
	v_mul_f32_e32 v190, v129, v190
	v_cvt_pk_bf16_f32 v190, v190, s0
	v_cndmask_b32_e64 v190, 0, v190, s[48:49]
	v_mul_f32_e32 v191, v243, v191
	v_mul_f32_e32 v191, v129, v191
	v_cvt_pk_bf16_f32 v191, v191, s0
	v_cndmask_b32_e64 v191, 0, v191, s[46:47]
	ds_write_b16 v94, v188 offset:62464
	ds_write_b16 v94, v189 offset:62608
	ds_write_b16 v94, v190 offset:62752
	ds_write_b16 v94, v191 offset:62896
	v_sub_f32_e32 v192, v132, v130
	v_mul_f32_e32 v192, 0x3fb8aa3b, v192
	v_exp_f32_e32 v192, v192
	v_sub_f32_e32 v193, v133, v130
	v_mul_f32_e32 v193, 0x3fb8aa3b, v193
	v_exp_f32_e32 v193, v193
	v_sub_f32_e32 v194, v134, v130
	v_mul_f32_e32 v194, 0x3fb8aa3b, v194
	v_exp_f32_e32 v194, v194
	v_sub_f32_e32 v195, v135, v130
	v_mul_f32_e32 v195, 0x3fb8aa3b, v195
	v_exp_f32_e32 v195, v195
	v_mul_f32_e32 v192, v244, v192
	v_mul_f32_e32 v192, v131, v192
	v_cvt_pk_bf16_f32 v192, v192, s0
	v_cndmask_b32_e64 v192, 0, v192, s[44:45]
	v_mul_f32_e32 v193, v245, v193
	v_mul_f32_e32 v193, v131, v193
	v_cvt_pk_bf16_f32 v193, v193, s0
	v_cndmask_b32_e64 v193, 0, v193, s[42:43]
	v_mul_f32_e32 v194, v246, v194
	v_mul_f32_e32 v194, v131, v194
	v_cvt_pk_bf16_f32 v194, v194, s0
	v_cndmask_b32_e64 v194, 0, v194, s[40:41]
	v_mul_f32_e32 v195, v247, v195
	v_mul_f32_e32 v195, v131, v195
	v_cvt_pk_bf16_f32 v195, v195, s0
	v_cndmask_b32_e64 v195, 0, v195, s[38:39]
	ds_write_b16 v94, v192 offset:62496
	ds_write_b16 v94, v193 offset:62640
	ds_write_b16 v94, v194 offset:62784
	ds_write_b16 v94, v195 offset:62928
	s_waitcnt lgkmcnt(0)
	s_barrier
	ds_read_b128 v[62:65], v91 offset:62464
	ds_read_b128 v[42:45], v91 offset:53248
	ds_read_b128 v[66:69], v91 offset:62528
	ds_read_b128 v[38:41], v91 offset:53312
	v_add_u32_e32 v121, v114, v103
	v_add_u32_e32 v124, v114, v100
	v_add_u32_e32 v123, s18, v113
	ds_read_b128 v[140:143], v121
	ds_read_b128 v[144:147], v121 offset:64
	ds_read_b128 v[148:151], v121 offset:128
	ds_read_b128 v[152:155], v121 offset:192
	ds_read_b128 v[156:159], v124
	ds_read_b128 v[160:163], v124 offset:64
	ds_read_b128 v[164:167], v124 offset:128
	ds_read_b128 v[168:171], v124 offset:192
	ds_read_b128 v[172:175], v123
	ds_read_b128 v[176:179], v90 offset:53248
	ds_read_b128 v[180:183], v90 offset:53312
	v_add_u32_e32 v120, s19, v89
	s_movk_i32 s27, 0x100
	v_cmp_gt_i32_e32 vcc, s27, v120
	s_movk_i32 s28, 0xc00
	v_mov_b32_e32 v84, s6
	v_add_u32_e32 v78, 0xffffff00, v120
	v_cndmask_b32_e32 v79, v252, v234, vcc
	v_cndmask_b32_e32 v78, v78, v120, vcc
	v_mov_b32_e32 v85, s7
	v_add3_u32 v79, v117, v79, s15
	v_cndmask_b32_e32 v80, v84, v85, vcc
	v_cndmask_b32_e64 v78, v79, v78, s[36:37]
	v_add_u32_e32 v78, v78, v80
	v_add_u32_e32 v80, 1, v120
	v_cmp_gt_i32_e32 vcc, s27, v80
	v_add_u32_e32 v81, 0xffffff01, v120
	v_mad_i64_i32 v[78:79], s[4:5], v78, s28, v[70:71]
	v_cndmask_b32_e32 v82, v252, v234, vcc
	v_add_u32_e32 v82, v117, v82
	v_cndmask_b32_e32 v80, v81, v80, vcc
	v_add3_u32 v82, v82, s15, -1
	v_cndmask_b32_e64 v80, v82, v80, s[36:37]
	v_add_u32_e32 v82, 2, v120
	v_cndmask_b32_e32 v81, v84, v85, vcc
	v_cmp_gt_i32_e32 vcc, s27, v82
	v_add_u32_e32 v83, 0xffffff02, v120
	v_cndmask_b32_e32 v124, v252, v234, vcc
	v_add_u32_e32 v124, v117, v124
	v_cndmask_b32_e32 v82, v83, v82, vcc
	v_add3_u32 v124, v124, s15, -2
	v_add_u32_e32 v80, v80, v81
	v_cndmask_b32_e64 v82, v124, v82, s[36:37]
	v_add_u32_e32 v124, 3, v120
	v_mad_i64_i32 v[80:81], s[4:5], v80, s28, v[70:71]
	v_cndmask_b32_e32 v83, v84, v85, vcc
	v_cmp_gt_i32_e32 vcc, s27, v124
	v_add_u32_e32 v120, 0xffffff03, v120
	v_cndmask_b32_e32 v125, v252, v234, vcc
	v_cndmask_b32_e32 v84, v84, v85, vcc
	v_add_u32_e32 v85, v117, v125
	v_cndmask_b32_e32 v120, v120, v124, vcc
	v_add3_u32 v85, v85, s15, -3
	v_cndmask_b32_e64 v85, v85, v120, s[36:37]
	v_add_u32_e32 v82, v82, v83
	v_add_u32_e32 v84, v85, v84
	v_mad_i64_i32 v[82:83], s[4:5], v82, s28, v[70:71]
	v_mad_i64_i32 v[84:85], s[4:5], v84, s28, v[70:71]
	v_add_u32_e32 v120, v114, v100
	s_add_i32 s19, s19, 64
	s_add_i32 s26, s26, 1
	s_sub_i32 s15, s15, 64
	s_waitcnt lgkmcnt(0)
	ds_read_b128 v[184:187], v88 offset:53248
	ds_read_b128 v[188:191], v88 offset:53312
	ds_read_b128 v[192:195], v87 offset:34816
	ds_read_b128 v[196:199], v87 offset:34880
	ds_read_b128 v[200:203], v87 offset:37120
	ds_read_b128 v[204:207], v87 offset:37184
	ds_read_b128 v[208:211], v87 offset:39424
	ds_read_b128 v[212:215], v87 offset:39488
	ds_read_b128 v[216:219], v87 offset:41728
	ds_read_b128 v[220:223], v87 offset:41792
	v_mfma_f32_16x16x32_bf16 v[240:243], v[58:61], v[140:143], 0
	v_mfma_f32_16x16x32_bf16 v[244:247], v[58:61], v[156:159], 0
	v_mfma_f32_16x16x32_bf16 v[240:243], v[54:57], v[144:147], v[240:243]
	v_mfma_f32_16x16x32_bf16 v[244:247], v[54:57], v[160:163], v[244:247]
	v_mfma_f32_16x16x32_bf16 v[240:243], v[50:53], v[148:151], v[240:243]
	v_mfma_f32_16x16x32_bf16 v[244:247], v[50:53], v[164:167], v[244:247]
	v_mfma_f32_16x16x32_bf16 v[240:243], v[46:49], v[152:155], v[240:243]
	v_mfma_f32_16x16x32_bf16 v[244:247], v[46:49], v[168:171], v[244:247]
	v_mul_f32_e32 v172, 0x3fb8aa3b, v172
	v_mul_f32_e32 v173, 0x3fb8aa3b, v173
	v_mul_f32_e32 v174, 0x3fb8aa3b, v174
	v_mul_f32_e32 v175, 0x3fb8aa3b, v175
	v_exp_f32_e32 v172, v172
	v_exp_f32_e32 v173, v173
	v_exp_f32_e32 v174, v174
	v_exp_f32_e32 v175, v175
	v_mul_f32_e32 v124, 0x3fb8aa3b, v119
	v_exp_f32_e32 v124, v124
	s_nop 0
	v_pk_mul_f32 v[16:17], v[16:17], v[124:125] op_sel_hi:[1,0]
	v_pk_mul_f32 v[14:15], v[14:15], v[124:125] op_sel_hi:[1,0]
	v_pk_mul_f32 v[12:13], v[12:13], v[124:125] op_sel_hi:[1,0]
	v_pk_mul_f32 v[10:11], v[10:11], v[124:125] op_sel_hi:[1,0]
	v_pk_mul_f32 v[8:9], v[8:9], v[124:125] op_sel_hi:[1,0]
	v_pk_mul_f32 v[6:7], v[6:7], v[124:125] op_sel_hi:[1,0]
	v_pk_mul_f32 v[4:5], v[4:5], v[124:125] op_sel_hi:[1,0]
	v_pk_mul_f32 v[2:3], v[2:3], v[124:125] op_sel_hi:[1,0]
	v_pk_mul_f32 v[240:241], v[240:241], v[172:173]
	v_pk_mul_f32 v[242:243], v[242:243], v[174:175]
	v_pk_mul_f32 v[244:245], v[244:245], v[172:173]
	v_pk_mul_f32 v[246:247], v[246:247], v[174:175]
	s_nop 1
	v_mfma_f32_16x16x32_bf16 v[240:243], v[62:65], v[176:179], v[240:243]
	v_mfma_f32_16x16x32_bf16 v[240:243], v[66:69], v[180:183], v[240:243]
	s_waitcnt lgkmcnt(8)
	v_mfma_f32_16x16x32_bf16 v[244:247], v[62:65], v[184:187], v[244:247]
	v_mfma_f32_16x16x32_bf16 v[244:247], v[66:69], v[188:191], v[244:247]
	s_waitcnt lgkmcnt(0)
	v_mfma_f32_16x16x32_bf16 v[14:17], v[42:45], v[192:195], v[14:17]
	v_mfma_f32_16x16x32_bf16 v[14:17], v[38:41], v[196:199], v[14:17]
	v_mfma_f32_16x16x32_bf16 v[10:13], v[42:45], v[200:203], v[10:13]
	v_mfma_f32_16x16x32_bf16 v[10:13], v[38:41], v[204:207], v[10:13]
	v_mfma_f32_16x16x32_bf16 v[6:9], v[42:45], v[208:211], v[6:9]
	v_mfma_f32_16x16x32_bf16 v[6:9], v[38:41], v[212:215], v[6:9]
	v_mfma_f32_16x16x32_bf16 v[2:5], v[42:45], v[216:219], v[2:5]
	v_mfma_f32_16x16x32_bf16 v[2:5], v[38:41], v[220:223], v[2:5]
	global_store_dword v[78:79], v240, off
	global_store_dword v[80:81], v241, off
	global_store_dword v[82:83], v242, off
	global_store_dword v[84:85], v243, off
	global_store_dword v[78:79], v244, off offset:64
	global_store_dword v[80:81], v245, off offset:64
	global_store_dword v[82:83], v246, off offset:64
	global_store_dword v[84:85], v247, off offset:64
	s_cmpk_eq_i32 s19, 0x8c0
	s_barrier
	v_cvt_pk_bf16_f32 v38, v14, s0
	ds_write_b16 v0, v38
	v_cvt_pk_bf16_f32 v38, v15, s0
	ds_write_b16 v0, v38 offset:272
	v_cvt_pk_bf16_f32 v38, v16, s0
	ds_write_b16 v0, v38 offset:544
	v_cvt_pk_bf16_f32 v38, v17, s0
	ds_write_b16 v0, v38 offset:816
	v_cvt_pk_bf16_f32 v38, v10, s0
	ds_write_b16 v0, v38 offset:32
	v_cvt_pk_bf16_f32 v38, v11, s0
	ds_write_b16 v0, v38 offset:304
	v_cvt_pk_bf16_f32 v38, v12, s0
	ds_write_b16 v0, v38 offset:576
	v_cvt_pk_bf16_f32 v38, v13, s0
	ds_write_b16 v0, v38 offset:848
	v_cvt_pk_bf16_f32 v38, v6, s0
	ds_write_b16 v0, v38 offset:64
	v_cvt_pk_bf16_f32 v38, v7, s0
	ds_write_b16 v0, v38 offset:336
	v_cvt_pk_bf16_f32 v38, v8, s0
	ds_write_b16 v0, v38 offset:608
	v_cvt_pk_bf16_f32 v38, v9, s0
	ds_write_b16 v0, v38 offset:880
	v_cvt_pk_bf16_f32 v38, v2, s0
	ds_write_b16 v0, v38 offset:96
	v_cvt_pk_bf16_f32 v38, v3, s0
	ds_write_b16 v0, v38 offset:368
	v_cvt_pk_bf16_f32 v38, v4, s0
	ds_write_b16 v0, v38 offset:640
	v_cvt_pk_bf16_f32 v38, v5, s0
	ds_write_b16 v0, v38 offset:912
	s_cbranch_scc1 .LBB0_934
	s_branch .LBB0_910

.LBB0_1013:
	s_mul_i32 s4, s19, 0x1200000
	s_ashr_i32 s5, s14, 4
	s_add_u32 s24, s2, s4
	s_addc_u32 s25, s3, 0
	s_cmp_lt_i32 s8, 4
	s_cselect_b64 s[16:17], -1, 0
	s_lshl_b32 s6, s8, 9
	s_cmp_eq_u32 s19, 0
	s_cselect_b64 s[36:37], -1, 0
	s_lshl_b32 s4, s8, 4
	s_mul_hi_i32 s21, s5, 0x900
	s_mul_i32 s20, s5, 0x900
	s_ashr_i32 s5, s4, 31
	s_lshl_b32 s8, s9, 8
	s_add_u32 s8, s24, s8
	s_addc_u32 s19, s25, 0
	s_lshl_b64 s[4:5], s[4:5], 2
	v_and_b32_e32 v0, 15, v86
	s_add_u32 s4, s8, s4
	v_ashrrev_i32_e32 v2, 2, v86
	s_addc_u32 s5, s19, s5
	v_lshlrev_b32_e32 v0, 2, v0
	v_and_b32_e32 v122, -4, v2
	v_lshl_add_u64 v[2:3], s[4:5], 0, v[0:1]
	s_mov_b64 s[4:5], 0x4e700000
	v_lshl_add_u64 v[102:103], v[2:3], 0, s[4:5]
	s_movk_i32 s4, 0xd40
	v_cmp_gt_i32_e64 s[38:39], s4, v138
	s_movk_i32 s4, 0xc40
	v_cmp_gt_i32_e64 s[40:41], s4, v138
	s_movk_i32 s4, 0xb40
	v_cmp_gt_i32_e64 s[42:43], s4, v138
	s_movk_i32 s4, 0xa40
	v_cmp_gt_i32_e64 s[44:45], s4, v138
	s_movk_i32 s4, 0x940
	v_cmp_gt_i32_e64 s[46:47], s4, v138
	s_movk_i32 s4, 0x840
	v_cmp_gt_i32_e64 s[48:49], s4, v138
	s_movk_i32 s4, 0x740
	v_cmp_gt_i32_e64 s[50:51], s4, v138
	s_movk_i32 s4, 0x640
	v_cmp_gt_i32_e64 s[52:53], s4, v138
	s_movk_i32 s4, 0x540
	v_cmp_gt_i32_e64 s[54:55], s4, v138
	s_movk_i32 s4, 0x440
	v_cmp_gt_i32_e64 s[56:57], s4, v138
	s_movk_i32 s4, 0x340
	v_cmp_gt_i32_e64 s[58:59], s4, v138
	s_movk_i32 s4, 0x240
	v_cmp_gt_i32_e64 s[60:61], s4, v138
	s_movk_i32 s4, 0x140
	v_cmp_gt_i32_e64 s[62:63], s4, v138
	s_add_i32 s4, s15, s18
	s_add_i32 s4, s4, s9
	s_mul_hi_i32 s5, s4, 0x1b9000
	s_mul_i32 s4, s4, 0x1b9000
	s_add_u32 s4, s2, s4
	v_ashrrev_i32_e32 v101, 31, v100
	s_addc_u32 s5, s3, s5
	v_lshl_add_u64 v[2:3], v[100:101], 4, s[4:5]
	s_mov_b64 s[4:5], 0x4440c400
	v_lshl_add_u64 v[104:105], v[2:3], 0, s[4:5]
	v_mov_b32_e32 v2, v1
	v_mov_b32_e32 v3, v1
	v_mov_b32_e32 v0, v1
	v_mov_b64_e32 v[58:59], v[2:3]
	v_mov_b64_e32 v[62:63], v[2:3]
	v_mov_b64_e32 v[66:67], v[2:3]
	v_mov_b64_e32 v[70:71], v[2:3]
	v_lshlrev_b32_e32 v120, 3, v86
	v_and_b32_e32 v121, -16, v86
	s_mov_b32 s7, 0
	v_sub_u32_e32 v101, 0xffffffcd, v122
	v_mov_b64_e32 v[56:57], v[0:1]
	v_mov_b64_e32 v[60:61], v[0:1]
	v_mov_b64_e32 v[64:65], v[0:1]
	v_mov_b64_e32 v[68:69], v[0:1]
	s_mov_b32 s8, 0
	s_waitcnt lgkmcnt(0)
	s_barrier
	s_cmp_lt_i32 s96, 4
	s_cbranch_scc1 .LBB0_1016
	v_lshlrev_b32_e32 v2, 4, v86
	v_lshlrev_b32_e32 v3, 4, v100
	v_add_u32_e32 v0, 0xc400, v3
	s_nop 1
	v_readfirstlane_b32 s100, v104
	v_readfirstlane_b32 s101, v105
	s_nop 4
	global_load_dwordx4 v[4:7], v2, s[100:101]
	s_add_u32 s100, s100, 0x1000
	s_addc_u32 s101, s101, 0
	global_load_dwordx4 v[8:11], v2, s[100:101]
	s_add_u32 s100, s100, 0x1000
	s_addc_u32 s101, s101, 0
	global_load_dwordx4 v[12:15], v2, s[100:101]
	s_add_u32 s100, s100, 0x1000
	s_addc_u32 s101, s101, 0
	global_load_dwordx4 v[16:19], v2, s[100:101]
	s_add_u32 s100, s100, 0x1000
	s_addc_u32 s101, s101, 0
	global_load_dwordx4 v[20:23], v2, s[100:101]
	s_add_u32 s100, s100, 0x1000
	s_addc_u32 s101, s101, 0
	global_load_dwordx4 v[24:27], v2, s[100:101]
	s_add_u32 s100, s100, 0x1000
	s_addc_u32 s101, s101, 0
	global_load_dwordx4 v[28:31], v2, s[100:101]
	s_add_u32 s100, s100, 0x1000
	s_addc_u32 s101, s101, 0
	global_load_dwordx4 v[32:35], v2, s[100:101]
	s_add_u32 s100, s100, 0x1000
	s_addc_u32 s101, s101, 0
	global_load_dwordx4 v[36:39], v2, s[100:101]
	s_add_u32 s100, s100, 0x1000
	s_addc_u32 s101, s101, 0
	global_load_dwordx4 v[40:43], v2, s[100:101]
	s_add_u32 s100, s100, 0x1000
	s_addc_u32 s101, s101, 0
	global_load_dwordx4 v[44:47], v2, s[100:101]
	s_add_u32 s100, s100, 0x1000
	s_addc_u32 s101, s101, 0
	global_load_dwordx4 v[48:51], v2, s[100:101]
	s_add_u32 s100, s100, 0x1000
	s_addc_u32 s101, s101, 0
	s_cmp_eq_u32 s96, 4
	s_cbranch_scc0 .Lrwl_i12_1
	global_load_dwordx4 v[52:55], v2, s[100:101]
.Lrwl_i12_1:
	s_add_u32 s100, s100, 0x400
	s_addc_u32 s101, s101, 0
	global_load_dwordx4 v[180:183], v2, s[100:101]
	s_add_u32 s100, s100, 0x1000
	s_addc_u32 s101, s101, 0
	global_load_dwordx4 v[184:187], v2, s[100:101]
	s_add_u32 s100, s100, 0x1000
	s_addc_u32 s101, s101, 0
	global_load_dwordx4 v[188:191], v2, s[100:101]
	s_add_u32 s100, s100, 0x1000
	s_addc_u32 s101, s101, 0
	global_load_dwordx4 v[192:195], v2, s[100:101]
	s_add_u32 s100, s100, 0x1000
	s_addc_u32 s101, s101, 0
	global_load_dwordx4 v[196:199], v2, s[100:101]
	s_add_u32 s100, s100, 0x1000
	s_addc_u32 s101, s101, 0
	global_load_dwordx4 v[200:203], v2, s[100:101]
	s_add_u32 s100, s100, 0x1000
	s_addc_u32 s101, s101, 0
	global_load_dwordx4 v[204:207], v2, s[100:101]
	s_add_u32 s100, s100, 0x1000
	s_addc_u32 s101, s101, 0
	global_load_dwordx4 v[208:211], v2, s[100:101]
	s_add_u32 s100, s100, 0x1000
	s_addc_u32 s101, s101, 0
	global_load_dwordx4 v[212:215], v2, s[100:101]
	s_add_u32 s100, s100, 0x1000
	s_addc_u32 s101, s101, 0
	global_load_dwordx4 v[216:219], v2, s[100:101]
	s_add_u32 s100, s100, 0x1000
	s_addc_u32 s101, s101, 0
	global_load_dwordx4 v[220:223], v2, s[100:101]
	s_add_u32 s100, s100, 0x1000
	s_addc_u32 s101, s101, 0
	global_load_dwordx4 v[240:243], v2, s[100:101]
	s_add_u32 s100, s100, 0x1000
	s_addc_u32 s101, s101, 0
	s_cmp_eq_u32 s96, 4
	s_cbranch_scc0 .Lrwl_i12_2
	global_load_dwordx4 v[244:247], v2, s[100:101]
.Lrwl_i12_2:
	s_add_u32 s100, s100, 0x400
	s_addc_u32 s101, s101, 0
	s_movk_i32 s7, 16
.Lrwl_loop_3:
	s_waitcnt vmcnt(12)
	ds_write_b128 v0, v[4:7]
	ds_write_b128 v0, v[8:11] offset:4096
	ds_write_b128 v0, v[12:15] offset:8192
	ds_write_b128 v0, v[16:19] offset:12288
	ds_write_b128 v0, v[20:23] offset:16384
	ds_write_b128 v0, v[24:27] offset:20480
	ds_write_b128 v0, v[28:31] offset:24576
	ds_write_b128 v0, v[32:35] offset:28672
	ds_write_b128 v0, v[36:39] offset:32768
	ds_write_b128 v0, v[40:43] offset:36864
	ds_write_b128 v0, v[44:47] offset:40960
	ds_write_b128 v0, v[48:51] offset:45056
	s_cmp_eq_u32 s96, 4
	s_cbranch_scc0 .Lrwl_c12_4
	ds_write_b128 v0, v[52:55] offset:49152
.Lrwl_c12_4:
	s_waitcnt lgkmcnt(0)
	global_load_dwordx4 v[4:7], v2, s[100:101]
	s_add_u32 s100, s100, 0x1000
	s_addc_u32 s101, s101, 0
	global_load_dwordx4 v[8:11], v2, s[100:101]
	s_add_u32 s100, s100, 0x1000
	s_addc_u32 s101, s101, 0
	global_load_dwordx4 v[12:15], v2, s[100:101]
	s_add_u32 s100, s100, 0x1000
	s_addc_u32 s101, s101, 0
	global_load_dwordx4 v[16:19], v2, s[100:101]
	s_add_u32 s100, s100, 0x1000
	s_addc_u32 s101, s101, 0
	global_load_dwordx4 v[20:23], v2, s[100:101]
	s_add_u32 s100, s100, 0x1000
	s_addc_u32 s101, s101, 0
	global_load_dwordx4 v[24:27], v2, s[100:101]
	s_add_u32 s100, s100, 0x1000
	s_addc_u32 s101, s101, 0
	global_load_dwordx4 v[28:31], v2, s[100:101]
	s_add_u32 s100, s100, 0x1000
	s_addc_u32 s101, s101, 0
	global_load_dwordx4 v[32:35], v2, s[100:101]
	s_add_u32 s100, s100, 0x1000
	s_addc_u32 s101, s101, 0
	global_load_dwordx4 v[36:39], v2, s[100:101]
	s_add_u32 s100, s100, 0x1000
	s_addc_u32 s101, s101, 0
	global_load_dwordx4 v[40:43], v2, s[100:101]
	s_add_u32 s100, s100, 0x1000
	s_addc_u32 s101, s101, 0
	global_load_dwordx4 v[44:47], v2, s[100:101]
	s_add_u32 s100, s100, 0x1000
	s_addc_u32 s101, s101, 0
	global_load_dwordx4 v[48:51], v2, s[100:101]
	s_add_u32 s100, s100, 0x1000
	s_addc_u32 s101, s101, 0
	s_cmp_eq_u32 s96, 4
	s_cbranch_scc0 .Lrwl_i12_5
	global_load_dwordx4 v[52:55], v2, s[100:101]
.Lrwl_i12_5:
	s_add_u32 s100, s100, 0x400
	s_addc_u32 s101, s101, 0
	s_barrier
	s_waitcnt vmcnt(12)
	ds_write_b128 v3, v[180:183]
	ds_write_b128 v3, v[184:187] offset:4096
	ds_write_b128 v3, v[188:191] offset:8192
	ds_write_b128 v3, v[192:195] offset:12288
	ds_write_b128 v3, v[196:199] offset:16384
	ds_write_b128 v3, v[200:203] offset:20480
	ds_write_b128 v3, v[204:207] offset:24576
	ds_write_b128 v3, v[208:211] offset:28672
	ds_write_b128 v3, v[212:215] offset:32768
	ds_write_b128 v3, v[216:219] offset:36864
	ds_write_b128 v3, v[220:223] offset:40960
	ds_write_b128 v3, v[240:243] offset:45056
	s_cmp_eq_u32 s96, 4
	s_cbranch_scc0 .Lrwl_c12_6
	ds_write_b128 v3, v[244:247] offset:49152
.Lrwl_c12_6:
	s_waitcnt lgkmcnt(0)
	global_load_dwordx4 v[180:183], v2, s[100:101]
	s_add_u32 s100, s100, 0x1000
	s_addc_u32 s101, s101, 0
	global_load_dwordx4 v[184:187], v2, s[100:101]
	s_add_u32 s100, s100, 0x1000
	s_addc_u32 s101, s101, 0
	global_load_dwordx4 v[188:191], v2, s[100:101]
	s_add_u32 s100, s100, 0x1000
	s_addc_u32 s101, s101, 0
	global_load_dwordx4 v[192:195], v2, s[100:101]
	s_add_u32 s100, s100, 0x1000
	s_addc_u32 s101, s101, 0
	global_load_dwordx4 v[196:199], v2, s[100:101]
	s_add_u32 s100, s100, 0x1000
	s_addc_u32 s101, s101, 0
	global_load_dwordx4 v[200:203], v2, s[100:101]
	s_add_u32 s100, s100, 0x1000
	s_addc_u32 s101, s101, 0
	global_load_dwordx4 v[204:207], v2, s[100:101]
	s_add_u32 s100, s100, 0x1000
	s_addc_u32 s101, s101, 0
	global_load_dwordx4 v[208:211], v2, s[100:101]
	s_add_u32 s100, s100, 0x1000
	s_addc_u32 s101, s101, 0
	global_load_dwordx4 v[212:215], v2, s[100:101]
	s_add_u32 s100, s100, 0x1000
	s_addc_u32 s101, s101, 0
	global_load_dwordx4 v[216:219], v2, s[100:101]
	s_add_u32 s100, s100, 0x1000
	s_addc_u32 s101, s101, 0
	global_load_dwordx4 v[220:223], v2, s[100:101]
	s_add_u32 s100, s100, 0x1000
	s_addc_u32 s101, s101, 0
	global_load_dwordx4 v[240:243], v2, s[100:101]
	s_add_u32 s100, s100, 0x1000
	s_addc_u32 s101, s101, 0
	s_cmp_eq_u32 s96, 4
	s_cbranch_scc0 .Lrwl_i12_7
	global_load_dwordx4 v[244:247], v2, s[100:101]
.Lrwl_i12_7:
	s_add_u32 s100, s100, 0x400
	s_addc_u32 s101, s101, 0
	s_barrier
	s_sub_u32 s7, s7, 1
	s_cmp_lg_u32 s7, 0
	s_cbranch_scc1 .Lrwl_loop_3
	s_waitcnt vmcnt(12)
	ds_write_b128 v0, v[4:7]
	ds_write_b128 v0, v[8:11] offset:4096
	ds_write_b128 v0, v[12:15] offset:8192
	ds_write_b128 v0, v[16:19] offset:12288
	ds_write_b128 v0, v[20:23] offset:16384
	ds_write_b128 v0, v[24:27] offset:20480
	ds_write_b128 v0, v[28:31] offset:24576
	ds_write_b128 v0, v[32:35] offset:28672
	ds_write_b128 v0, v[36:39] offset:32768
	ds_write_b128 v0, v[40:43] offset:36864
	ds_write_b128 v0, v[44:47] offset:40960
	ds_write_b128 v0, v[48:51] offset:45056
	s_cmp_eq_u32 s96, 4
	s_cbranch_scc0 .Lrwl_c12_8
	ds_write_b128 v0, v[52:55] offset:49152

.Lrwl_c12_10:
	s_waitcnt lgkmcnt(0)
	s_barrier
	s_waitcnt vmcnt(0)
	ds_write_b128 v0, v[4:7]
	ds_write_b128 v0, v[8:11] offset:4096
	ds_write_b128 v0, v[12:15] offset:8192
	ds_write_b128 v0, v[16:19] offset:12288
	ds_write_b128 v0, v[20:23] offset:16384
	ds_write_b128 v0, v[24:27] offset:20480
	ds_write_b128 v0, v[28:31] offset:24576
	ds_write_b128 v0, v[32:35] offset:28672
	ds_write_b128 v0, v[36:39] offset:32768
	ds_write_b128 v0, v[40:43] offset:36864
	ds_write_b128 v0, v[44:47] offset:40960
	ds_write_b128 v0, v[48:51] offset:45056
	s_cmp_eq_u32 s96, 4
	s_cbranch_scc0 .Lrwl_c12_11
	ds_write_b128 v0, v[52:55] offset:49152
.Lrwl_c12_11:
	s_waitcnt lgkmcnt(0)
	s_barrier
	s_barrier
	s_branch .LBB0_1075

.LBB0_1626:
	s_add_i32 s34, s20, 0xffffe000
	s_lshl_b64 s[4:5], s[34:35], 12
	v_lshl_add_u64 v[172:173], v[222:223], 0, s[4:5]
	s_nop 1
	v_readfirstlane_b32 s100, v172
	v_readfirstlane_b32 s101, v173
	s_nop 1
	v_subrev_u32_e32 v224, s100, v172
	s_nop 4
	global_load_dwordx2 v[130:131], v224, s[100:101]
	s_add_u32 s100, s100, 0x400000
	s_addc_u32 s101, s101, 0
	global_load_dwordx2 v[132:133], v224, s[100:101]
	s_add_u32 s100, s100, 0x400000
	s_addc_u32 s101, s101, 0
	global_load_dwordx2 v[134:135], v224, s[100:101]
	s_add_u32 s100, s100, 0x400000
	s_addc_u32 s101, s101, 0
	global_load_dwordx2 v[136:137], v224, s[100:101]
	s_add_u32 s100, s100, 0x400000
	s_addc_u32 s101, s101, 0
	global_load_dwordx2 v[138:139], v224, s[100:101]
	s_add_u32 s100, s100, 0x400000
	s_addc_u32 s101, s101, 0
	global_load_dwordx2 v[140:141], v224, s[100:101]
	s_add_u32 s100, s100, 0x400000
	s_addc_u32 s101, s101, 0
	global_load_dwordx2 v[142:143], v224, s[100:101]
	s_add_u32 s100, s100, 0x400000
	s_addc_u32 s101, s101, 0
	global_load_dwordx2 v[144:145], v224, s[100:101]
	s_sub_u32 s100, s100, 0x1c00000
	s_subb_u32 s101, s101, 0
	global_load_dwordx2 v[146:147], v224, s[100:101] offset:512
	s_add_u32 s100, s100, 0x400000
	s_addc_u32 s101, s101, 0
	global_load_dwordx2 v[148:149], v224, s[100:101] offset:512
	s_add_u32 s100, s100, 0x400000
	s_addc_u32 s101, s101, 0
	global_load_dwordx2 v[150:151], v224, s[100:101] offset:512
	s_add_u32 s100, s100, 0x400000
	s_addc_u32 s101, s101, 0
	global_load_dwordx2 v[152:153], v224, s[100:101] offset:512
	s_add_u32 s100, s100, 0x400000
	s_addc_u32 s101, s101, 0
	global_load_dwordx2 v[154:155], v224, s[100:101] offset:512
	s_add_u32 s100, s100, 0x400000
	s_addc_u32 s101, s101, 0
	global_load_dwordx2 v[156:157], v224, s[100:101] offset:512
	s_add_u32 s100, s100, 0x400000
	s_addc_u32 s101, s101, 0
	global_load_dwordx2 v[158:159], v224, s[100:101] offset:512
	s_add_u32 s100, s100, 0x400000
	s_addc_u32 s101, s101, 0
	global_load_dwordx2 v[160:161], v224, s[100:101] offset:512
	s_sub_u32 s100, s100, 0x1c00000
	s_subb_u32 s101, s101, 0
	global_load_dwordx2 v[162:163], v224, s[100:101] offset:1024
	s_add_u32 s100, s100, 0x400000
	s_addc_u32 s101, s101, 0
	global_load_dwordx2 v[164:165], v224, s[100:101] offset:1024
	s_add_u32 s100, s100, 0x400000
	s_addc_u32 s101, s101, 0
	global_load_dwordx2 v[166:167], v224, s[100:101] offset:1024
	s_add_u32 s100, s100, 0x400000
	s_addc_u32 s101, s101, 0
	global_load_dwordx2 v[168:169], v224, s[100:101] offset:1024
	s_add_u32 s100, s100, 0x400000
	s_addc_u32 s101, s101, 0
	global_load_dwordx2 v[170:171], v224, s[100:101] offset:1024
	s_add_u32 s100, s100, 0x400000
	s_addc_u32 s101, s101, 0
	global_load_dwordx2 v[172:173], v224, s[100:101] offset:1024
	s_add_u32 s100, s100, 0x400000
	s_addc_u32 s101, s101, 0
	global_load_dwordx2 v[174:175], v224, s[100:101] offset:1024
	s_add_u32 s100, s100, 0x400000
	s_addc_u32 s101, s101, 0
	global_load_dwordx2 v[176:177], v224, s[100:101] offset:1024
	s_sub_u32 s100, s100, 0x1c00000
	s_subb_u32 s101, s101, 0
	global_load_dwordx2 v[178:179], v224, s[100:101] offset:1536
	s_add_u32 s100, s100, 0x400000
	s_addc_u32 s101, s101, 0
	global_load_dwordx2 v[180:181], v224, s[100:101] offset:1536
	s_add_u32 s100, s100, 0x400000
	s_addc_u32 s101, s101, 0
	global_load_dwordx2 v[182:183], v224, s[100:101] offset:1536
	s_add_u32 s100, s100, 0x400000
	s_addc_u32 s101, s101, 0
	global_load_dwordx2 v[184:185], v224, s[100:101] offset:1536
	s_add_u32 s100, s100, 0x400000
	s_addc_u32 s101, s101, 0
	global_load_dwordx2 v[186:187], v224, s[100:101] offset:1536
	s_add_u32 s100, s100, 0x400000
	s_addc_u32 s101, s101, 0
	global_load_dwordx2 v[188:189], v224, s[100:101] offset:1536
	s_add_u32 s100, s100, 0x400000
	s_addc_u32 s101, s101, 0
	global_load_dwordx2 v[190:191], v224, s[100:101] offset:1536
	s_add_u32 s100, s100, 0x400000
	s_addc_u32 s101, s101, 0
	global_load_dwordx2 v[192:193], v224, s[100:101] offset:1536
	s_sub_u32 s100, s100, 0x1c00000
	s_subb_u32 s101, s101, 0
	s_waitcnt vmcnt(24)
	v_lshlrev_b32_e32 v232, 16, v130
	v_and_b32_e32 v233, 0xffff0000, v130
	v_lshlrev_b32_e32 v240, 16, v131
	v_and_b32_e32 v241, 0xffff0000, v131
	v_add_f32_e32 v232, 0, v232
	v_add_f32_e32 v233, 0, v233
	v_add_f32_e32 v240, 0, v240
	v_add_f32_e32 v241, 0, v241
	v_lshlrev_b32_e32 v225, 16, v132
	v_and_b32_e32 v132, 0xffff0000, v132
	v_add_f32_e32 v232, v232, v225
	v_add_f32_e32 v233, v233, v132
	v_lshlrev_b32_e32 v225, 16, v133
	v_and_b32_e32 v133, 0xffff0000, v133
	v_add_f32_e32 v240, v240, v225
	v_add_f32_e32 v241, v241, v133
	v_lshlrev_b32_e32 v225, 16, v134
	v_and_b32_e32 v134, 0xffff0000, v134
	v_add_f32_e32 v232, v232, v225
	v_add_f32_e32 v233, v233, v134
	v_lshlrev_b32_e32 v225, 16, v135
	v_and_b32_e32 v135, 0xffff0000, v135
	v_add_f32_e32 v240, v240, v225
	v_add_f32_e32 v241, v241, v135
	v_lshlrev_b32_e32 v225, 16, v136
	v_and_b32_e32 v136, 0xffff0000, v136
	v_add_f32_e32 v232, v232, v225
	v_add_f32_e32 v233, v233, v136
	v_lshlrev_b32_e32 v225, 16, v137
	v_and_b32_e32 v137, 0xffff0000, v137
	v_add_f32_e32 v240, v240, v225
	v_add_f32_e32 v241, v241, v137
	v_lshlrev_b32_e32 v225, 16, v138
	v_and_b32_e32 v138, 0xffff0000, v138
	v_add_f32_e32 v232, v232, v225
	v_add_f32_e32 v233, v233, v138
	v_lshlrev_b32_e32 v225, 16, v139
	v_and_b32_e32 v139, 0xffff0000, v139
	v_add_f32_e32 v240, v240, v225
	v_add_f32_e32 v241, v241, v139
	v_lshlrev_b32_e32 v225, 16, v140
	v_and_b32_e32 v140, 0xffff0000, v140
	v_add_f32_e32 v232, v232, v225
	v_add_f32_e32 v233, v233, v140
	v_lshlrev_b32_e32 v225, 16, v141
	v_and_b32_e32 v141, 0xffff0000, v141
	v_add_f32_e32 v240, v240, v225
	v_add_f32_e32 v241, v241, v141
	v_lshlrev_b32_e32 v225, 16, v142
	v_and_b32_e32 v142, 0xffff0000, v142
	v_add_f32_e32 v232, v232, v225
	v_add_f32_e32 v233, v233, v142
	v_lshlrev_b32_e32 v225, 16, v143
	v_and_b32_e32 v143, 0xffff0000, v143
	v_add_f32_e32 v240, v240, v225
	v_add_f32_e32 v241, v241, v143
	v_lshlrev_b32_e32 v225, 16, v144
	v_and_b32_e32 v144, 0xffff0000, v144
	v_add_f32_e32 v232, v232, v225
	v_add_f32_e32 v233, v233, v144
	v_lshlrev_b32_e32 v225, 16, v145
	v_and_b32_e32 v145, 0xffff0000, v145
	v_add_f32_e32 v240, v240, v225
	v_add_f32_e32 v241, v241, v145
	v_mov_b32_e32 v130, v232
	v_mov_b32_e32 v131, v233
	v_mov_b32_e32 v132, v240
	v_mov_b32_e32 v133, v241
	s_waitcnt vmcnt(16)
	v_lshlrev_b32_e32 v134, 16, v146
	v_and_b32_e32 v135, 0xffff0000, v146
	v_lshlrev_b32_e32 v136, 16, v147
	v_and_b32_e32 v137, 0xffff0000, v147
	v_add_f32_e32 v134, 0, v134
	v_add_f32_e32 v135, 0, v135
	v_add_f32_e32 v136, 0, v136
	v_add_f32_e32 v137, 0, v137
	v_lshlrev_b32_e32 v225, 16, v148
	v_and_b32_e32 v148, 0xffff0000, v148
	v_add_f32_e32 v134, v134, v225
	v_add_f32_e32 v135, v135, v148
	v_lshlrev_b32_e32 v225, 16, v149
	v_and_b32_e32 v149, 0xffff0000, v149
	v_add_f32_e32 v136, v136, v225
	v_add_f32_e32 v137, v137, v149
	v_lshlrev_b32_e32 v225, 16, v150
	v_and_b32_e32 v150, 0xffff0000, v150
	v_add_f32_e32 v134, v134, v225
	v_add_f32_e32 v135, v135, v150
	v_lshlrev_b32_e32 v225, 16, v151
	v_and_b32_e32 v151, 0xffff0000, v151
	v_add_f32_e32 v136, v136, v225
	v_add_f32_e32 v137, v137, v151
	v_lshlrev_b32_e32 v225, 16, v152
	v_and_b32_e32 v152, 0xffff0000, v152
	v_add_f32_e32 v134, v134, v225
	v_add_f32_e32 v135, v135, v152
	v_lshlrev_b32_e32 v225, 16, v153
	v_and_b32_e32 v153, 0xffff0000, v153
	v_add_f32_e32 v136, v136, v225
	v_add_f32_e32 v137, v137, v153
	v_lshlrev_b32_e32 v225, 16, v154
	v_and_b32_e32 v154, 0xffff0000, v154
	v_add_f32_e32 v134, v134, v225
	v_add_f32_e32 v135, v135, v154
	v_lshlrev_b32_e32 v225, 16, v155
	v_and_b32_e32 v155, 0xffff0000, v155
	v_add_f32_e32 v136, v136, v225
	v_add_f32_e32 v137, v137, v155
	v_lshlrev_b32_e32 v225, 16, v156
	v_and_b32_e32 v156, 0xffff0000, v156
	v_add_f32_e32 v134, v134, v225
	v_add_f32_e32 v135, v135, v156
	v_lshlrev_b32_e32 v225, 16, v157
	v_and_b32_e32 v157, 0xffff0000, v157
	v_add_f32_e32 v136, v136, v225
	v_add_f32_e32 v137, v137, v157
	v_lshlrev_b32_e32 v225, 16, v158
	v_and_b32_e32 v158, 0xffff0000, v158
	v_add_f32_e32 v134, v134, v225
	v_add_f32_e32 v135, v135, v158
	v_lshlrev_b32_e32 v225, 16, v159
	v_and_b32_e32 v159, 0xffff0000, v159
	v_add_f32_e32 v136, v136, v225
	v_add_f32_e32 v137, v137, v159
	v_lshlrev_b32_e32 v225, 16, v160
	v_and_b32_e32 v160, 0xffff0000, v160
	v_add_f32_e32 v134, v134, v225
	v_add_f32_e32 v135, v135, v160
	v_lshlrev_b32_e32 v225, 16, v161
	v_and_b32_e32 v161, 0xffff0000, v161
	v_add_f32_e32 v136, v136, v225
	v_add_f32_e32 v137, v137, v161
	global_load_dwordx2 v[146:147], v224, s[100:101] offset:2048
	s_add_u32 s100, s100, 0x400000
	s_addc_u32 s101, s101, 0
	global_load_dwordx2 v[148:149], v224, s[100:101] offset:2048
	s_add_u32 s100, s100, 0x400000
	s_addc_u32 s101, s101, 0
	global_load_dwordx2 v[150:151], v224, s[100:101] offset:2048
	s_add_u32 s100, s100, 0x400000
	s_addc_u32 s101, s101, 0
	global_load_dwordx2 v[152:153], v224, s[100:101] offset:2048
	s_add_u32 s100, s100, 0x400000
	s_addc_u32 s101, s101, 0
	global_load_dwordx2 v[154:155], v224, s[100:101] offset:2048
	s_add_u32 s100, s100, 0x400000
	s_addc_u32 s101, s101, 0
	global_load_dwordx2 v[156:157], v224, s[100:101] offset:2048
	s_add_u32 s100, s100, 0x400000
	s_addc_u32 s101, s101, 0
	global_load_dwordx2 v[158:159], v224, s[100:101] offset:2048
	s_add_u32 s100, s100, 0x400000
	s_addc_u32 s101, s101, 0
	global_load_dwordx2 v[160:161], v224, s[100:101] offset:2048
	s_sub_u32 s100, s100, 0x1c00000
	s_subb_u32 s101, s101, 0
	s_waitcnt vmcnt(16)
	v_lshlrev_b32_e32 v138, 16, v162
	v_and_b32_e32 v139, 0xffff0000, v162
	v_lshlrev_b32_e32 v140, 16, v163
	v_and_b32_e32 v141, 0xffff0000, v163
	v_add_f32_e32 v138, 0, v138
	v_add_f32_e32 v139, 0, v139
	v_add_f32_e32 v140, 0, v140
	v_add_f32_e32 v141, 0, v141
	v_lshlrev_b32_e32 v225, 16, v164
	v_and_b32_e32 v164, 0xffff0000, v164
	v_add_f32_e32 v138, v138, v225
	v_add_f32_e32 v139, v139, v164
	v_lshlrev_b32_e32 v225, 16, v165
	v_and_b32_e32 v165, 0xffff0000, v165
	v_add_f32_e32 v140, v140, v225
	v_add_f32_e32 v141, v141, v165
	v_lshlrev_b32_e32 v225, 16, v166
	v_and_b32_e32 v166, 0xffff0000, v166
	v_add_f32_e32 v138, v138, v225
	v_add_f32_e32 v139, v139, v166
	v_lshlrev_b32_e32 v225, 16, v167
	v_and_b32_e32 v167, 0xffff0000, v167
	v_add_f32_e32 v140, v140, v225
	v_add_f32_e32 v141, v141, v167
	v_lshlrev_b32_e32 v225, 16, v168
	v_and_b32_e32 v168, 0xffff0000, v168
	v_add_f32_e32 v138, v138, v225
	v_add_f32_e32 v139, v139, v168
	v_lshlrev_b32_e32 v225, 16, v169
	v_and_b32_e32 v169, 0xffff0000, v169
	v_add_f32_e32 v140, v140, v225
	v_add_f32_e32 v141, v141, v169
	v_lshlrev_b32_e32 v225, 16, v170
	v_and_b32_e32 v170, 0xffff0000, v170
	v_add_f32_e32 v138, v138, v225
	v_add_f32_e32 v139, v139, v170
	v_lshlrev_b32_e32 v225, 16, v171
	v_and_b32_e32 v171, 0xffff0000, v171
	v_add_f32_e32 v140, v140, v225
	v_add_f32_e32 v141, v141, v171
	v_lshlrev_b32_e32 v225, 16, v172
	v_and_b32_e32 v172, 0xffff0000, v172
	v_add_f32_e32 v138, v138, v225
	v_add_f32_e32 v139, v139, v172
	v_lshlrev_b32_e32 v225, 16, v173
	v_and_b32_e32 v173, 0xffff0000, v173
	v_add_f32_e32 v140, v140, v225
	v_add_f32_e32 v141, v141, v173
	v_lshlrev_b32_e32 v225, 16, v174
	v_and_b32_e32 v174, 0xffff0000, v174
	v_add_f32_e32 v138, v138, v225
	v_add_f32_e32 v139, v139, v174
	v_lshlrev_b32_e32 v225, 16, v175
	v_and_b32_e32 v175, 0xffff0000, v175
	v_add_f32_e32 v140, v140, v225
	v_add_f32_e32 v141, v141, v175
	v_lshlrev_b32_e32 v225, 16, v176
	v_and_b32_e32 v176, 0xffff0000, v176
	v_add_f32_e32 v138, v138, v225
	v_add_f32_e32 v139, v139, v176
	v_lshlrev_b32_e32 v225, 16, v177
	v_and_b32_e32 v177, 0xffff0000, v177
	v_add_f32_e32 v140, v140, v225
	v_add_f32_e32 v141, v141, v177
	global_load_dwordx2 v[162:163], v224, s[100:101] offset:2560
	s_add_u32 s100, s100, 0x400000
	s_addc_u32 s101, s101, 0
	global_load_dwordx2 v[164:165], v224, s[100:101] offset:2560
	s_add_u32 s100, s100, 0x400000
	s_addc_u32 s101, s101, 0
	global_load_dwordx2 v[166:167], v224, s[100:101] offset:2560
	s_add_u32 s100, s100, 0x400000
	s_addc_u32 s101, s101, 0
	global_load_dwordx2 v[168:169], v224, s[100:101] offset:2560
	s_add_u32 s100, s100, 0x400000
	s_addc_u32 s101, s101, 0
	global_load_dwordx2 v[170:171], v224, s[100:101] offset:2560
	s_add_u32 s100, s100, 0x400000
	s_addc_u32 s101, s101, 0
	global_load_dwordx2 v[172:173], v224, s[100:101] offset:2560
	s_add_u32 s100, s100, 0x400000
	s_addc_u32 s101, s101, 0
	global_load_dwordx2 v[174:175], v224, s[100:101] offset:2560
	s_add_u32 s100, s100, 0x400000
	s_addc_u32 s101, s101, 0
	global_load_dwordx2 v[176:177], v224, s[100:101] offset:2560
	s_sub_u32 s100, s100, 0x1c00000
	s_subb_u32 s101, s101, 0
	s_waitcnt vmcnt(16)
	v_lshlrev_b32_e32 v142, 16, v178
	v_and_b32_e32 v143, 0xffff0000, v178
	v_lshlrev_b32_e32 v144, 16, v179
	v_and_b32_e32 v145, 0xffff0000, v179
	v_add_f32_e32 v142, 0, v142
	v_add_f32_e32 v143, 0, v143
	v_add_f32_e32 v144, 0, v144
	v_add_f32_e32 v145, 0, v145
	v_lshlrev_b32_e32 v225, 16, v180
	v_and_b32_e32 v180, 0xffff0000, v180
	v_add_f32_e32 v142, v142, v225
	v_add_f32_e32 v143, v143, v180
	v_lshlrev_b32_e32 v225, 16, v181
	v_and_b32_e32 v181, 0xffff0000, v181
	v_add_f32_e32 v144, v144, v225
	v_add_f32_e32 v145, v145, v181
	v_lshlrev_b32_e32 v225, 16, v182
	v_and_b32_e32 v182, 0xffff0000, v182
	v_add_f32_e32 v142, v142, v225
	v_add_f32_e32 v143, v143, v182
	v_lshlrev_b32_e32 v225, 16, v183
	v_and_b32_e32 v183, 0xffff0000, v183
	v_add_f32_e32 v144, v144, v225
	v_add_f32_e32 v145, v145, v183
	v_lshlrev_b32_e32 v225, 16, v184
	v_and_b32_e32 v184, 0xffff0000, v184
	v_add_f32_e32 v142, v142, v225
	v_add_f32_e32 v143, v143, v184
	v_lshlrev_b32_e32 v225, 16, v185
	v_and_b32_e32 v185, 0xffff0000, v185
	v_add_f32_e32 v144, v144, v225
	v_add_f32_e32 v145, v145, v185
	v_lshlrev_b32_e32 v225, 16, v186
	v_and_b32_e32 v186, 0xffff0000, v186
	v_add_f32_e32 v142, v142, v225
	v_add_f32_e32 v143, v143, v186
	v_lshlrev_b32_e32 v225, 16, v187
	v_and_b32_e32 v187, 0xffff0000, v187
	v_add_f32_e32 v144, v144, v225
	v_add_f32_e32 v145, v145, v187
	v_lshlrev_b32_e32 v225, 16, v188
	v_and_b32_e32 v188, 0xffff0000, v188
	v_add_f32_e32 v142, v142, v225
	v_add_f32_e32 v143, v143, v188
	v_lshlrev_b32_e32 v225, 16, v189
	v_and_b32_e32 v189, 0xffff0000, v189
	v_add_f32_e32 v144, v144, v225
	v_add_f32_e32 v145, v145, v189
	v_lshlrev_b32_e32 v225, 16, v190
	v_and_b32_e32 v190, 0xffff0000, v190
	v_add_f32_e32 v142, v142, v225
	v_add_f32_e32 v143, v143, v190
	v_lshlrev_b32_e32 v225, 16, v191
	v_and_b32_e32 v191, 0xffff0000, v191
	v_add_f32_e32 v144, v144, v225
	v_add_f32_e32 v145, v145, v191
	v_lshlrev_b32_e32 v225, 16, v192
	v_and_b32_e32 v192, 0xffff0000, v192
	v_add_f32_e32 v142, v142, v225
	v_add_f32_e32 v143, v143, v192
	v_lshlrev_b32_e32 v225, 16, v193
	v_and_b32_e32 v193, 0xffff0000, v193
	v_add_f32_e32 v144, v144, v225
	v_add_f32_e32 v145, v145, v193
	global_load_dwordx2 v[178:179], v224, s[100:101] offset:3072
	s_add_u32 s100, s100, 0x400000
	s_addc_u32 s101, s101, 0
	global_load_dwordx2 v[180:181], v224, s[100:101] offset:3072
	s_add_u32 s100, s100, 0x400000
	s_addc_u32 s101, s101, 0
	global_load_dwordx2 v[182:183], v224, s[100:101] offset:3072
	s_add_u32 s100, s100, 0x400000
	s_addc_u32 s101, s101, 0
	global_load_dwordx2 v[184:185], v224, s[100:101] offset:3072
	s_add_u32 s100, s100, 0x400000
	s_addc_u32 s101, s101, 0
	global_load_dwordx2 v[186:187], v224, s[100:101] offset:3072
	s_add_u32 s100, s100, 0x400000
	s_addc_u32 s101, s101, 0
	global_load_dwordx2 v[188:189], v224, s[100:101] offset:3072
	s_add_u32 s100, s100, 0x400000
	s_addc_u32 s101, s101, 0
	global_load_dwordx2 v[190:191], v224, s[100:101] offset:3072
	s_add_u32 s100, s100, 0x400000
	s_addc_u32 s101, s101, 0
	global_load_dwordx2 v[192:193], v224, s[100:101] offset:3072
	s_sub_u32 s100, s100, 0x1c00000
	s_subb_u32 s101, s101, 0
	s_waitcnt vmcnt(16)
	v_lshlrev_b32_e32 v232, 16, v146
	v_and_b32_e32 v233, 0xffff0000, v146
	v_lshlrev_b32_e32 v240, 16, v147
	v_and_b32_e32 v241, 0xffff0000, v147
	v_add_f32_e32 v232, 0, v232
	v_add_f32_e32 v233, 0, v233
	v_add_f32_e32 v240, 0, v240
	v_add_f32_e32 v241, 0, v241
	v_lshlrev_b32_e32 v225, 16, v148
	v_and_b32_e32 v148, 0xffff0000, v148
	v_add_f32_e32 v232, v232, v225
	v_add_f32_e32 v233, v233, v148
	v_lshlrev_b32_e32 v225, 16, v149
	v_and_b32_e32 v149, 0xffff0000, v149
	v_add_f32_e32 v240, v240, v225
	v_add_f32_e32 v241, v241, v149
	v_lshlrev_b32_e32 v225, 16, v150
	v_and_b32_e32 v150, 0xffff0000, v150
	v_add_f32_e32 v232, v232, v225
	v_add_f32_e32 v233, v233, v150
	v_lshlrev_b32_e32 v225, 16, v151
	v_and_b32_e32 v151, 0xffff0000, v151
	v_add_f32_e32 v240, v240, v225
	v_add_f32_e32 v241, v241, v151
	v_lshlrev_b32_e32 v225, 16, v152
	v_and_b32_e32 v152, 0xffff0000, v152
	v_add_f32_e32 v232, v232, v225
	v_add_f32_e32 v233, v233, v152
	v_lshlrev_b32_e32 v225, 16, v153
	v_and_b32_e32 v153, 0xffff0000, v153
	v_add_f32_e32 v240, v240, v225
	v_add_f32_e32 v241, v241, v153
	v_lshlrev_b32_e32 v225, 16, v154
	v_and_b32_e32 v154, 0xffff0000, v154
	v_add_f32_e32 v232, v232, v225
	v_add_f32_e32 v233, v233, v154
	v_lshlrev_b32_e32 v225, 16, v155
	v_and_b32_e32 v155, 0xffff0000, v155
	v_add_f32_e32 v240, v240, v225
	v_add_f32_e32 v241, v241, v155
	v_lshlrev_b32_e32 v225, 16, v156
	v_and_b32_e32 v156, 0xffff0000, v156
	v_add_f32_e32 v232, v232, v225
	v_add_f32_e32 v233, v233, v156
	v_lshlrev_b32_e32 v225, 16, v157
	v_and_b32_e32 v157, 0xffff0000, v157
	v_add_f32_e32 v240, v240, v225
	v_add_f32_e32 v241, v241, v157
	v_lshlrev_b32_e32 v225, 16, v158
	v_and_b32_e32 v158, 0xffff0000, v158
	v_add_f32_e32 v232, v232, v225
	v_add_f32_e32 v233, v233, v158
	v_lshlrev_b32_e32 v225, 16, v159
	v_and_b32_e32 v159, 0xffff0000, v159
	v_add_f32_e32 v240, v240, v225
	v_add_f32_e32 v241, v241, v159
	v_lshlrev_b32_e32 v225, 16, v160
	v_and_b32_e32 v160, 0xffff0000, v160
	v_add_f32_e32 v232, v232, v225
	v_add_f32_e32 v233, v233, v160
	v_lshlrev_b32_e32 v225, 16, v161
	v_and_b32_e32 v161, 0xffff0000, v161
	v_add_f32_e32 v240, v240, v225
	v_add_f32_e32 v241, v241, v161
	v_mov_b32_e32 v146, v232
	v_mov_b32_e32 v147, v233
	v_mov_b32_e32 v148, v240
	v_mov_b32_e32 v149, v241
	s_waitcnt vmcnt(8)
	v_lshlrev_b32_e32 v150, 16, v162
	v_and_b32_e32 v151, 0xffff0000, v162
	v_lshlrev_b32_e32 v152, 16, v163
	v_and_b32_e32 v153, 0xffff0000, v163
	v_add_f32_e32 v150, 0, v150
	v_add_f32_e32 v151, 0, v151
	v_add_f32_e32 v152, 0, v152
	v_add_f32_e32 v153, 0, v153
	v_lshlrev_b32_e32 v225, 16, v164
	v_and_b32_e32 v164, 0xffff0000, v164
	v_add_f32_e32 v150, v150, v225
	v_add_f32_e32 v151, v151, v164
	v_lshlrev_b32_e32 v225, 16, v165
	v_and_b32_e32 v165, 0xffff0000, v165
	v_add_f32_e32 v152, v152, v225
	v_add_f32_e32 v153, v153, v165
	v_lshlrev_b32_e32 v225, 16, v166
	v_and_b32_e32 v166, 0xffff0000, v166
	v_add_f32_e32 v150, v150, v225
	v_add_f32_e32 v151, v151, v166
	v_lshlrev_b32_e32 v225, 16, v167
	v_and_b32_e32 v167, 0xffff0000, v167
	v_add_f32_e32 v152, v152, v225
	v_add_f32_e32 v153, v153, v167
	v_lshlrev_b32_e32 v225, 16, v168
	v_and_b32_e32 v168, 0xffff0000, v168
	v_add_f32_e32 v150, v150, v225
	v_add_f32_e32 v151, v151, v168
	v_lshlrev_b32_e32 v225, 16, v169
	v_and_b32_e32 v169, 0xffff0000, v169
	v_add_f32_e32 v152, v152, v225
	v_add_f32_e32 v153, v153, v169
	v_lshlrev_b32_e32 v225, 16, v170
	v_and_b32_e32 v170, 0xffff0000, v170
	v_add_f32_e32 v150, v150, v225
	v_add_f32_e32 v151, v151, v170
	v_lshlrev_b32_e32 v225, 16, v171
	v_and_b32_e32 v171, 0xffff0000, v171
	v_add_f32_e32 v152, v152, v225
	v_add_f32_e32 v153, v153, v171
	v_lshlrev_b32_e32 v225, 16, v172
	v_and_b32_e32 v172, 0xffff0000, v172
	v_add_f32_e32 v150, v150, v225
	v_add_f32_e32 v151, v151, v172
	v_lshlrev_b32_e32 v225, 16, v173
	v_and_b32_e32 v173, 0xffff0000, v173
	v_add_f32_e32 v152, v152, v225
	v_add_f32_e32 v153, v153, v173
	v_lshlrev_b32_e32 v225, 16, v174
	v_and_b32_e32 v174, 0xffff0000, v174
	v_add_f32_e32 v150, v150, v225
	v_add_f32_e32 v151, v151, v174
	v_lshlrev_b32_e32 v225, 16, v175
	v_and_b32_e32 v175, 0xffff0000, v175
	v_add_f32_e32 v152, v152, v225
	v_add_f32_e32 v153, v153, v175
	v_lshlrev_b32_e32 v225, 16, v176
	v_and_b32_e32 v176, 0xffff0000, v176
	v_add_f32_e32 v150, v150, v225
	v_add_f32_e32 v151, v151, v176
	v_lshlrev_b32_e32 v225, 16, v177
	v_and_b32_e32 v177, 0xffff0000, v177
	v_add_f32_e32 v152, v152, v225
	v_add_f32_e32 v153, v153, v177
	global_load_dwordx2 v[162:163], v224, s[100:101] offset:3584
	s_add_u32 s100, s100, 0x400000
	s_addc_u32 s101, s101, 0
	global_load_dwordx2 v[164:165], v224, s[100:101] offset:3584
	s_add_u32 s100, s100, 0x400000
	s_addc_u32 s101, s101, 0
	global_load_dwordx2 v[166:167], v224, s[100:101] offset:3584
	s_add_u32 s100, s100, 0x400000
	s_addc_u32 s101, s101, 0
	global_load_dwordx2 v[168:169], v224, s[100:101] offset:3584
	s_add_u32 s100, s100, 0x400000
	s_addc_u32 s101, s101, 0
	global_load_dwordx2 v[170:171], v224, s[100:101] offset:3584
	s_add_u32 s100, s100, 0x400000
	s_addc_u32 s101, s101, 0
	global_load_dwordx2 v[172:173], v224, s[100:101] offset:3584
	s_add_u32 s100, s100, 0x400000
	s_addc_u32 s101, s101, 0
	global_load_dwordx2 v[174:175], v224, s[100:101] offset:3584
	s_add_u32 s100, s100, 0x400000
	s_addc_u32 s101, s101, 0
	global_load_dwordx2 v[176:177], v224, s[100:101] offset:3584
	s_sub_u32 s100, s100, 0x1c00000
	s_subb_u32 s101, s101, 0
	s_waitcnt vmcnt(8)
	v_lshlrev_b32_e32 v154, 16, v178
	v_and_b32_e32 v155, 0xffff0000, v178
	v_lshlrev_b32_e32 v156, 16, v179
	v_and_b32_e32 v157, 0xffff0000, v179
	v_add_f32_e32 v154, 0, v154
	v_add_f32_e32 v155, 0, v155
	v_add_f32_e32 v156, 0, v156
	v_add_f32_e32 v157, 0, v157
	v_lshlrev_b32_e32 v225, 16, v180
	v_and_b32_e32 v180, 0xffff0000, v180
	v_add_f32_e32 v154, v154, v225
	v_add_f32_e32 v155, v155, v180
	v_lshlrev_b32_e32 v225, 16, v181
	v_and_b32_e32 v181, 0xffff0000, v181
	v_add_f32_e32 v156, v156, v225
	v_add_f32_e32 v157, v157, v181
	v_lshlrev_b32_e32 v225, 16, v182
	v_and_b32_e32 v182, 0xffff0000, v182
	v_add_f32_e32 v154, v154, v225
	v_add_f32_e32 v155, v155, v182
	v_lshlrev_b32_e32 v225, 16, v183
	v_and_b32_e32 v183, 0xffff0000, v183
	v_add_f32_e32 v156, v156, v225
	v_add_f32_e32 v157, v157, v183
	v_lshlrev_b32_e32 v225, 16, v184
	v_and_b32_e32 v184, 0xffff0000, v184
	v_add_f32_e32 v154, v154, v225
	v_add_f32_e32 v155, v155, v184
	v_lshlrev_b32_e32 v225, 16, v185
	v_and_b32_e32 v185, 0xffff0000, v185
	v_add_f32_e32 v156, v156, v225
	v_add_f32_e32 v157, v157, v185
	v_lshlrev_b32_e32 v225, 16, v186
	v_and_b32_e32 v186, 0xffff0000, v186
	v_add_f32_e32 v154, v154, v225
	v_add_f32_e32 v155, v155, v186
	v_lshlrev_b32_e32 v225, 16, v187
	v_and_b32_e32 v187, 0xffff0000, v187
	v_add_f32_e32 v156, v156, v225
	v_add_f32_e32 v157, v157, v187
	v_lshlrev_b32_e32 v225, 16, v188
	v_and_b32_e32 v188, 0xffff0000, v188
	v_add_f32_e32 v154, v154, v225
	v_add_f32_e32 v155, v155, v188
	v_lshlrev_b32_e32 v225, 16, v189
	v_and_b32_e32 v189, 0xffff0000, v189
	v_add_f32_e32 v156, v156, v225
	v_add_f32_e32 v157, v157, v189
	v_lshlrev_b32_e32 v225, 16, v190
	v_and_b32_e32 v190, 0xffff0000, v190
	v_add_f32_e32 v154, v154, v225
	v_add_f32_e32 v155, v155, v190
	v_lshlrev_b32_e32 v225, 16, v191
	v_and_b32_e32 v191, 0xffff0000, v191
	v_add_f32_e32 v156, v156, v225
	v_add_f32_e32 v157, v157, v191
	v_lshlrev_b32_e32 v225, 16, v192
	v_and_b32_e32 v192, 0xffff0000, v192
	v_add_f32_e32 v154, v154, v225
	v_add_f32_e32 v155, v155, v192
	v_lshlrev_b32_e32 v225, 16, v193
	v_and_b32_e32 v193, 0xffff0000, v193
	v_add_f32_e32 v156, v156, v225
	v_add_f32_e32 v157, v157, v193
	s_waitcnt vmcnt(0)
	v_lshlrev_b32_e32 v158, 16, v162
	v_and_b32_e32 v159, 0xffff0000, v162
	v_lshlrev_b32_e32 v160, 16, v163
	v_and_b32_e32 v161, 0xffff0000, v163
	v_add_f32_e32 v158, 0, v158
	v_add_f32_e32 v159, 0, v159
	v_add_f32_e32 v160, 0, v160
	v_add_f32_e32 v161, 0, v161
	v_lshlrev_b32_e32 v225, 16, v164
	v_and_b32_e32 v164, 0xffff0000, v164
	v_add_f32_e32 v158, v158, v225
	v_add_f32_e32 v159, v159, v164
	v_lshlrev_b32_e32 v225, 16, v165
	v_and_b32_e32 v165, 0xffff0000, v165
	v_add_f32_e32 v160, v160, v225
	v_add_f32_e32 v161, v161, v165
	v_lshlrev_b32_e32 v225, 16, v166
	v_and_b32_e32 v166, 0xffff0000, v166
	v_add_f32_e32 v158, v158, v225
	v_add_f32_e32 v159, v159, v166
	v_lshlrev_b32_e32 v225, 16, v167
	v_and_b32_e32 v167, 0xffff0000, v167
	v_add_f32_e32 v160, v160, v225
	v_add_f32_e32 v161, v161, v167
	v_lshlrev_b32_e32 v225, 16, v168
	v_and_b32_e32 v168, 0xffff0000, v168
	v_add_f32_e32 v158, v158, v225
	v_add_f32_e32 v159, v159, v168
	v_lshlrev_b32_e32 v225, 16, v169
	v_and_b32_e32 v169, 0xffff0000, v169
	v_add_f32_e32 v160, v160, v225
	v_add_f32_e32 v161, v161, v169
	v_lshlrev_b32_e32 v225, 16, v170
	v_and_b32_e32 v170, 0xffff0000, v170
	v_add_f32_e32 v158, v158, v225
	v_add_f32_e32 v159, v159, v170
	v_lshlrev_b32_e32 v225, 16, v171
	v_and_b32_e32 v171, 0xffff0000, v171
	v_add_f32_e32 v160, v160, v225
	v_add_f32_e32 v161, v161, v171
	v_lshlrev_b32_e32 v225, 16, v172
	v_and_b32_e32 v172, 0xffff0000, v172
	v_add_f32_e32 v158, v158, v225
	v_add_f32_e32 v159, v159, v172
	v_lshlrev_b32_e32 v225, 16, v173
	v_and_b32_e32 v173, 0xffff0000, v173
	v_add_f32_e32 v160, v160, v225
	v_add_f32_e32 v161, v161, v173
	v_lshlrev_b32_e32 v225, 16, v174
	v_and_b32_e32 v174, 0xffff0000, v174
	v_add_f32_e32 v158, v158, v225
	v_add_f32_e32 v159, v159, v174
	v_lshlrev_b32_e32 v225, 16, v175
	v_and_b32_e32 v175, 0xffff0000, v175
	v_add_f32_e32 v160, v160, v225
	v_add_f32_e32 v161, v161, v175
	v_lshlrev_b32_e32 v225, 16, v176
	v_and_b32_e32 v176, 0xffff0000, v176
	v_add_f32_e32 v158, v158, v225
	v_add_f32_e32 v159, v159, v176
	v_lshlrev_b32_e32 v225, 16, v177
	v_and_b32_e32 v177, 0xffff0000, v177
	v_add_f32_e32 v160, v160, v225
	v_add_f32_e32 v161, v161, v177

.LBB0_1692:
	s_add_u32 s33, s4, 0x100
	s_addc_u32 s53, s5, 0
	s_ashr_i32 s25, s24, 31
	s_lshl_b64 s[6:7], s[24:25], 20
	s_add_u32 s30, s36, s6
	s_addc_u32 s31, s37, s7
	s_and_b64 s[6:7], s[34:35], exec
	s_cselect_b32 s25, s31, s17
	s_cselect_b32 s54, s30, s16
	s_ashr_i32 s21, s20, 31
	s_lshl_b64 s[6:7], s[20:21], 20
	s_add_u32 s28, s38, s6
	s_addc_u32 s29, s39, s7
	s_and_b64 s[6:7], s[34:35], exec
	s_cselect_b32 s21, s29, s5
	s_cselect_b32 s55, s28, s4
	s_add_u32 s4, s16, 0x80080
	s_addc_u32 s5, s17, 0
	v_lshl_add_u64 v[158:159], s[4:5], 0, v[154:155]
	v_lshl_add_u64 v[160:161], s[4:5], 0, v[156:157]
	s_mov_b32 s56, -2
	s_mov_b64 s[4:5], 0
.LBB0_1693:
	s_add_u32 s6, s16, s4
	s_addc_u32 s7, s17, s5
	s_add_u32 s6, s6, 0x100
	s_addc_u32 s7, s7, 0
	s_add_u32 s57, s33, s4
	s_addc_u32 s58, s53, s5
	s_add_i32 s59, 0, 0x10000
	s_cmpk_eq_i32 s4, 0xf00
	s_cselect_b32 s9, s25, s7
	s_cselect_b32 s8, s54, s6
	s_cselect_b32 s7, s21, s58
	s_cselect_b32 s6, s55, s57
	s_add_i32 s57, 0, 0x14000
	v_add_u32_e32 v176, s59, v162
	v_add_u32_e32 v192, s57, v162
	ds_read_b128 v[164:167], v176
	ds_read_b128 v[168:171], v176 offset:1024
	ds_read_b128 v[172:175], v176 offset:2048
	ds_read_b128 v[176:179], v176 offset:3072
	ds_read_b128 v[180:183], v192
	ds_read_b128 v[184:187], v192 offset:1024
	ds_read_b128 v[188:191], v192 offset:2048
	ds_read_b128 v[192:195], v192 offset:3072
	v_lshl_add_u64 v[224:225], v[158:159], 0, s[4:5]
	s_add_i32 m0, s3, 0xc000
	ds_read_b128 v[196:199], v163
	ds_read_b128 v[200:203], v163 offset:1024
	ds_read_b128 v[204:207], v163 offset:2048
	ds_read_b128 v[208:211], v163 offset:3072
	ds_read_b128 v[212:215], v163 offset:4096
	ds_read_b128 v[216:219], v163 offset:5120
	ds_read_b128 v[220:223], v163 offset:6144
	ds_read_b128 v[240:243], v163 offset:7168
	global_load_lds_dwordx4 v[224:225], off
	v_lshl_add_u64 v[224:225], v[160:161], 0, s[4:5]
	s_add_i32 m0, s3, 0xe000
	s_nop 0
	global_load_lds_dwordx4 v[224:225], off
	s_waitcnt vmcnt(8)
	s_waitcnt lgkmcnt(0)
	s_barrier
	s_setprio 1
	s_waitcnt lgkmcnt(0)
	v_mfma_f32_16x16x32_bf16 v[126:129], v[164:167], v[196:199], v[126:129]
	v_mfma_f32_16x16x32_bf16 v[122:125], v[172:175], v[196:199], v[122:125]
	v_mfma_f32_16x16x32_bf16 v[118:121], v[164:167], v[204:207], v[118:121]
	v_mfma_f32_16x16x32_bf16 v[114:117], v[172:175], v[204:207], v[114:117]
	v_mfma_f32_16x16x32_bf16 v[110:113], v[164:167], v[212:215], v[110:113]
	v_mfma_f32_16x16x32_bf16 v[106:109], v[172:175], v[212:215], v[106:109]
	v_mfma_f32_16x16x32_bf16 v[102:105], v[164:167], v[220:223], v[102:105]
	v_mfma_f32_16x16x32_bf16 v[98:101], v[172:175], v[220:223], v[98:101]
	v_mfma_f32_16x16x32_bf16 v[126:129], v[168:171], v[200:203], v[126:129]
	v_mfma_f32_16x16x32_bf16 v[122:125], v[176:179], v[200:203], v[122:125]
	v_mfma_f32_16x16x32_bf16 v[118:121], v[168:171], v[208:211], v[118:121]
	v_mfma_f32_16x16x32_bf16 v[114:117], v[176:179], v[208:211], v[114:117]
	v_mfma_f32_16x16x32_bf16 v[110:113], v[168:171], v[216:219], v[110:113]
	v_mfma_f32_16x16x32_bf16 v[106:109], v[176:179], v[216:219], v[106:109]
	v_mfma_f32_16x16x32_bf16 v[102:105], v[168:171], v[240:243], v[102:105]
	v_mfma_f32_16x16x32_bf16 v[98:101], v[176:179], v[240:243], v[98:101]
	s_setprio 0
	s_setprio 1
	v_mfma_f32_16x16x32_bf16 v[94:97], v[180:183], v[196:199], v[94:97]
	v_mfma_f32_16x16x32_bf16 v[90:93], v[188:191], v[196:199], v[90:93]
	v_mfma_f32_16x16x32_bf16 v[86:89], v[180:183], v[204:207], v[86:89]
	v_mfma_f32_16x16x32_bf16 v[82:85], v[188:191], v[204:207], v[82:85]
	v_mfma_f32_16x16x32_bf16 v[78:81], v[180:183], v[212:215], v[78:81]
	v_mfma_f32_16x16x32_bf16 v[74:77], v[188:191], v[212:215], v[74:77]
	v_mfma_f32_16x16x32_bf16 v[70:73], v[180:183], v[220:223], v[70:73]
	v_mfma_f32_16x16x32_bf16 v[66:69], v[188:191], v[220:223], v[66:69]
	v_mfma_f32_16x16x32_bf16 v[94:97], v[184:187], v[200:203], v[94:97]
	v_mfma_f32_16x16x32_bf16 v[90:93], v[192:195], v[200:203], v[90:93]
	v_mfma_f32_16x16x32_bf16 v[86:89], v[184:187], v[208:211], v[86:89]
	v_mfma_f32_16x16x32_bf16 v[82:85], v[192:195], v[208:211], v[82:85]
	v_mfma_f32_16x16x32_bf16 v[78:81], v[184:187], v[216:219], v[78:81]
	v_mfma_f32_16x16x32_bf16 v[74:77], v[192:195], v[216:219], v[74:77]
	v_mfma_f32_16x16x32_bf16 v[70:73], v[184:187], v[240:243], v[70:73]
	v_mfma_f32_16x16x32_bf16 v[66:69], v[192:195], v[240:243], v[66:69]
	s_setprio 0
	s_barrier
	s_add_i32 s58, s59, s40
	v_lshl_add_u64 v[224:225], s[6:7], 0, v[0:1]
	s_mov_b32 m0, s58
	ds_read_b128 v[196:199], v163 offset:16384
	ds_read_b128 v[200:203], v163 offset:17408
	ds_read_b128 v[204:207], v163 offset:18432
	ds_read_b128 v[208:211], v163 offset:19456
	ds_read_b128 v[212:215], v163 offset:20480
	ds_read_b128 v[216:219], v163 offset:21504
	ds_read_b128 v[220:223], v163 offset:22528
	ds_read_b128 v[240:243], v163 offset:23552
	global_load_lds_dwordx4 v[224:225], off
	s_add_i32 m0, s58, 0x2000
	s_add_u32 s58, s6, 0x80000
	v_lshl_add_u64 v[232:233], s[6:7], 0, v[130:131]
	s_addc_u32 s59, s7, 0
	s_add_i32 s57, s57, s40
	global_load_lds_dwordx4 v[232:233], off
	v_lshl_add_u64 v[244:245], s[58:59], 0, v[0:1]
	s_mov_b32 m0, s57
	v_lshl_add_u64 v[246:247], s[8:9], 0, v[132:133]
	global_load_lds_dwordx4 v[244:245], off
	v_lshl_add_u64 v[244:245], s[58:59], 0, v[130:131]
	s_add_i32 m0, s57, 0x2000
	s_nop 0
	global_load_lds_dwordx4 v[244:245], off
	v_lshl_add_u64 v[244:245], s[8:9], 0, v[134:135]
	s_mov_b32 m0, s3
	s_nop 0
	global_load_lds_dwordx4 v[244:245], off
	s_mov_b32 m0, s43
	s_nop 0
	global_load_lds_dwordx4 v[246:247], off
	s_waitcnt vmcnt(8)
	s_waitcnt lgkmcnt(0)
	s_barrier
	s_setprio 1
	s_waitcnt lgkmcnt(0)
	v_mfma_f32_16x16x32_bf16 v[62:65], v[164:167], v[196:199], v[62:65]
	v_mfma_f32_16x16x32_bf16 v[58:61], v[172:175], v[196:199], v[58:61]
	v_mfma_f32_16x16x32_bf16 v[54:57], v[164:167], v[204:207], v[54:57]
	v_mfma_f32_16x16x32_bf16 v[50:53], v[172:175], v[204:207], v[50:53]
	v_mfma_f32_16x16x32_bf16 v[46:49], v[164:167], v[212:215], v[46:49]
	v_mfma_f32_16x16x32_bf16 v[42:45], v[172:175], v[212:215], v[42:45]
	v_mfma_f32_16x16x32_bf16 v[38:41], v[164:167], v[220:223], v[38:41]
	v_mfma_f32_16x16x32_bf16 v[34:37], v[172:175], v[220:223], v[34:37]
	v_mfma_f32_16x16x32_bf16 v[62:65], v[168:171], v[200:203], v[62:65]
	v_mfma_f32_16x16x32_bf16 v[58:61], v[176:179], v[200:203], v[58:61]
	v_mfma_f32_16x16x32_bf16 v[54:57], v[168:171], v[208:211], v[54:57]
	v_mfma_f32_16x16x32_bf16 v[50:53], v[176:179], v[208:211], v[50:53]
	v_mfma_f32_16x16x32_bf16 v[46:49], v[168:171], v[216:219], v[46:49]
	v_mfma_f32_16x16x32_bf16 v[42:45], v[176:179], v[216:219], v[42:45]
	v_mfma_f32_16x16x32_bf16 v[38:41], v[168:171], v[240:243], v[38:41]
	v_mfma_f32_16x16x32_bf16 v[34:37], v[176:179], v[240:243], v[34:37]
	s_setprio 0
	s_setprio 1
	v_mfma_f32_16x16x32_bf16 v[30:33], v[180:183], v[196:199], v[30:33]
	v_mfma_f32_16x16x32_bf16 v[26:29], v[188:191], v[196:199], v[26:29]
	v_mfma_f32_16x16x32_bf16 v[22:25], v[180:183], v[204:207], v[22:25]
	v_mfma_f32_16x16x32_bf16 v[18:21], v[188:191], v[204:207], v[18:21]
	v_mfma_f32_16x16x32_bf16 v[14:17], v[180:183], v[212:215], v[14:17]
	v_mfma_f32_16x16x32_bf16 v[10:13], v[188:191], v[212:215], v[10:13]
	v_mfma_f32_16x16x32_bf16 v[6:9], v[180:183], v[220:223], v[6:9]
	v_mfma_f32_16x16x32_bf16 v[2:5], v[188:191], v[220:223], v[2:5]
	v_mfma_f32_16x16x32_bf16 v[30:33], v[184:187], v[200:203], v[30:33]
	v_mfma_f32_16x16x32_bf16 v[26:29], v[192:195], v[200:203], v[26:29]
	v_mfma_f32_16x16x32_bf16 v[22:25], v[184:187], v[208:211], v[22:25]
	v_mfma_f32_16x16x32_bf16 v[18:21], v[192:195], v[208:211], v[18:21]
	v_mfma_f32_16x16x32_bf16 v[14:17], v[184:187], v[216:219], v[14:17]
	v_mfma_f32_16x16x32_bf16 v[10:13], v[192:195], v[216:219], v[10:13]
	v_mfma_f32_16x16x32_bf16 v[6:9], v[184:187], v[240:243], v[6:9]
	v_mfma_f32_16x16x32_bf16 v[2:5], v[192:195], v[240:243], v[2:5]
	s_setprio 0
	s_barrier
	s_add_i32 s57, 0, 0x18000
	s_add_i32 s58, 0, 0x1c000
	v_add_u32_e32 v176, s57, v162
	v_add_u32_e32 v192, s58, v162
	ds_read_b128 v[164:167], v176
	ds_read_b128 v[168:171], v176 offset:1024
	ds_read_b128 v[172:175], v176 offset:2048
	ds_read_b128 v[176:179], v176 offset:3072
	ds_read_b128 v[180:183], v192
	ds_read_b128 v[184:187], v192 offset:1024
	ds_read_b128 v[188:191], v192 offset:2048
	ds_read_b128 v[192:195], v192 offset:3072
	s_add_u32 s8, s8, 0x80000
	s_addc_u32 s9, s9, 0
	s_mov_b32 m0, s44
	v_lshl_add_u64 v[248:249], s[8:9], 0, v[134:135]
	ds_read_b128 v[196:199], v163 offset:32768
	ds_read_b128 v[200:203], v163 offset:33792
	ds_read_b128 v[204:207], v163 offset:34816
	ds_read_b128 v[208:211], v163 offset:35840
	ds_read_b128 v[212:215], v163 offset:36864
	ds_read_b128 v[216:219], v163 offset:37888
	ds_read_b128 v[220:223], v163 offset:38912
	ds_read_b128 v[240:243], v163 offset:39936
	global_load_lds_dwordx4 v[248:249], off
	v_lshl_add_u64 v[248:249], s[8:9], 0, v[132:133]
	s_mov_b32 m0, s45
	s_nop 0
	global_load_lds_dwordx4 v[248:249], off
	s_waitcnt vmcnt(8)
	s_waitcnt lgkmcnt(0)
	s_barrier
	s_setprio 1
	s_waitcnt lgkmcnt(0)
	v_mfma_f32_16x16x32_bf16 v[126:129], v[164:167], v[196:199], v[126:129]
	v_mfma_f32_16x16x32_bf16 v[122:125], v[172:175], v[196:199], v[122:125]
	v_mfma_f32_16x16x32_bf16 v[118:121], v[164:167], v[204:207], v[118:121]
	v_mfma_f32_16x16x32_bf16 v[114:117], v[172:175], v[204:207], v[114:117]
	v_mfma_f32_16x16x32_bf16 v[110:113], v[164:167], v[212:215], v[110:113]
	v_mfma_f32_16x16x32_bf16 v[106:109], v[172:175], v[212:215], v[106:109]
	v_mfma_f32_16x16x32_bf16 v[102:105], v[164:167], v[220:223], v[102:105]
	v_mfma_f32_16x16x32_bf16 v[98:101], v[172:175], v[220:223], v[98:101]
	v_mfma_f32_16x16x32_bf16 v[126:129], v[168:171], v[200:203], v[126:129]
	v_mfma_f32_16x16x32_bf16 v[122:125], v[176:179], v[200:203], v[122:125]
	v_mfma_f32_16x16x32_bf16 v[118:121], v[168:171], v[208:211], v[118:121]
	v_mfma_f32_16x16x32_bf16 v[114:117], v[176:179], v[208:211], v[114:117]
	v_mfma_f32_16x16x32_bf16 v[110:113], v[168:171], v[216:219], v[110:113]
	v_mfma_f32_16x16x32_bf16 v[106:109], v[176:179], v[216:219], v[106:109]
	v_mfma_f32_16x16x32_bf16 v[102:105], v[168:171], v[240:243], v[102:105]
	v_mfma_f32_16x16x32_bf16 v[98:101], v[176:179], v[240:243], v[98:101]
	s_setprio 0
	s_setprio 1
	v_mfma_f32_16x16x32_bf16 v[94:97], v[180:183], v[196:199], v[94:97]
	v_mfma_f32_16x16x32_bf16 v[90:93], v[188:191], v[196:199], v[90:93]
	v_mfma_f32_16x16x32_bf16 v[86:89], v[180:183], v[204:207], v[86:89]
	v_mfma_f32_16x16x32_bf16 v[82:85], v[188:191], v[204:207], v[82:85]
	v_mfma_f32_16x16x32_bf16 v[78:81], v[180:183], v[212:215], v[78:81]
	v_mfma_f32_16x16x32_bf16 v[74:77], v[188:191], v[212:215], v[74:77]
	v_mfma_f32_16x16x32_bf16 v[70:73], v[180:183], v[220:223], v[70:73]
	v_mfma_f32_16x16x32_bf16 v[66:69], v[188:191], v[220:223], v[66:69]
	v_mfma_f32_16x16x32_bf16 v[94:97], v[184:187], v[200:203], v[94:97]
	v_mfma_f32_16x16x32_bf16 v[90:93], v[192:195], v[200:203], v[90:93]
	v_mfma_f32_16x16x32_bf16 v[86:89], v[184:187], v[208:211], v[86:89]
	v_mfma_f32_16x16x32_bf16 v[82:85], v[192:195], v[208:211], v[82:85]
	v_mfma_f32_16x16x32_bf16 v[78:81], v[184:187], v[216:219], v[78:81]
	v_mfma_f32_16x16x32_bf16 v[74:77], v[192:195], v[216:219], v[74:77]
	v_mfma_f32_16x16x32_bf16 v[70:73], v[184:187], v[240:243], v[70:73]
	v_mfma_f32_16x16x32_bf16 v[66:69], v[192:195], v[240:243], v[66:69]
	s_setprio 0
	s_barrier
	s_add_i32 s8, s57, s40
	v_lshl_add_u64 v[224:225], v[224:225], 0, s[22:23]
	s_mov_b32 m0, s8
	ds_read_b128 v[196:199], v163 offset:49152
	ds_read_b128 v[200:203], v163 offset:50176
	ds_read_b128 v[204:207], v163 offset:51200
	ds_read_b128 v[208:211], v163 offset:52224
	ds_read_b128 v[212:215], v163 offset:53248
	ds_read_b128 v[216:219], v163 offset:54272
	ds_read_b128 v[220:223], v163 offset:55296
	ds_read_b128 v[240:243], v163 offset:56320
	global_load_lds_dwordx4 v[224:225], off
	s_add_i32 m0, s8, 0x2000
	s_add_u32 s6, s6, 0x80080
	v_lshl_add_u64 v[224:225], v[232:233], 0, s[22:23]
	s_addc_u32 s7, s7, 0
	s_add_i32 s8, s58, s40
	global_load_lds_dwordx4 v[224:225], off
	v_lshl_add_u64 v[224:225], s[6:7], 0, v[0:1]
	s_mov_b32 m0, s8
	s_nop 0
	global_load_lds_dwordx4 v[224:225], off
	v_lshl_add_u64 v[224:225], s[6:7], 0, v[130:131]
	s_add_i32 m0, s8, 0x2000
	s_nop 0
	global_load_lds_dwordx4 v[224:225], off
	v_lshl_add_u64 v[224:225], v[244:245], 0, s[22:23]
	s_mov_b32 m0, s49
	s_nop 0
	global_load_lds_dwordx4 v[224:225], off
	v_lshl_add_u64 v[224:225], v[246:247], 0, s[22:23]
	s_mov_b32 m0, s50
	s_nop 0
	global_load_lds_dwordx4 v[224:225], off
	s_waitcnt vmcnt(8)
	s_waitcnt lgkmcnt(0)
	s_barrier
	s_setprio 1
	s_waitcnt lgkmcnt(0)
	v_mfma_f32_16x16x32_bf16 v[62:65], v[164:167], v[196:199], v[62:65]
	v_mfma_f32_16x16x32_bf16 v[58:61], v[172:175], v[196:199], v[58:61]
	v_mfma_f32_16x16x32_bf16 v[54:57], v[164:167], v[204:207], v[54:57]
	v_mfma_f32_16x16x32_bf16 v[50:53], v[172:175], v[204:207], v[50:53]
	v_mfma_f32_16x16x32_bf16 v[46:49], v[164:167], v[212:215], v[46:49]
	v_mfma_f32_16x16x32_bf16 v[42:45], v[172:175], v[212:215], v[42:45]
	v_mfma_f32_16x16x32_bf16 v[38:41], v[164:167], v[220:223], v[38:41]
	v_mfma_f32_16x16x32_bf16 v[34:37], v[172:175], v[220:223], v[34:37]
	v_mfma_f32_16x16x32_bf16 v[62:65], v[168:171], v[200:203], v[62:65]
	v_mfma_f32_16x16x32_bf16 v[58:61], v[176:179], v[200:203], v[58:61]
	v_mfma_f32_16x16x32_bf16 v[54:57], v[168:171], v[208:211], v[54:57]
	v_mfma_f32_16x16x32_bf16 v[50:53], v[176:179], v[208:211], v[50:53]
	v_mfma_f32_16x16x32_bf16 v[46:49], v[168:171], v[216:219], v[46:49]
	v_mfma_f32_16x16x32_bf16 v[42:45], v[176:179], v[216:219], v[42:45]
	v_mfma_f32_16x16x32_bf16 v[38:41], v[168:171], v[240:243], v[38:41]
	v_mfma_f32_16x16x32_bf16 v[34:37], v[176:179], v[240:243], v[34:37]
	s_setprio 0
	s_setprio 1
	v_mfma_f32_16x16x32_bf16 v[30:33], v[180:183], v[196:199], v[30:33]
	v_mfma_f32_16x16x32_bf16 v[26:29], v[188:191], v[196:199], v[26:29]
	v_mfma_f32_16x16x32_bf16 v[22:25], v[180:183], v[204:207], v[22:25]
	v_mfma_f32_16x16x32_bf16 v[18:21], v[188:191], v[204:207], v[18:21]
	v_mfma_f32_16x16x32_bf16 v[14:17], v[180:183], v[212:215], v[14:17]
	v_mfma_f32_16x16x32_bf16 v[10:13], v[188:191], v[212:215], v[10:13]
	v_mfma_f32_16x16x32_bf16 v[6:9], v[180:183], v[220:223], v[6:9]
	v_mfma_f32_16x16x32_bf16 v[2:5], v[188:191], v[220:223], v[2:5]
	v_mfma_f32_16x16x32_bf16 v[30:33], v[184:187], v[200:203], v[30:33]
	v_mfma_f32_16x16x32_bf16 v[26:29], v[192:195], v[200:203], v[26:29]
	v_mfma_f32_16x16x32_bf16 v[22:25], v[184:187], v[208:211], v[22:25]
	v_mfma_f32_16x16x32_bf16 v[18:21], v[192:195], v[208:211], v[18:21]
	v_mfma_f32_16x16x32_bf16 v[14:17], v[184:187], v[216:219], v[14:17]
	v_mfma_f32_16x16x32_bf16 v[10:13], v[192:195], v[216:219], v[10:13]
	v_mfma_f32_16x16x32_bf16 v[6:9], v[184:187], v[240:243], v[6:9]
	v_mfma_f32_16x16x32_bf16 v[2:5], v[192:195], v[240:243], v[2:5]
	s_setprio 0
	s_barrier
	s_add_i32 s56, s56, 2
	s_add_u32 s4, s4, 0x100
	s_addc_u32 s5, s5, 0
	s_cmp_gt_u32 s56, 29
	s_cbranch_scc0 .LBB0_1693
	s_and_b64 vcc, exec, s[12:13]
	s_cbranch_vccz .LBB0_1696
	s_barrier

.LBB0_1855:
	s_add_i32 s34, s16, 0xffffe000
	s_lshl_b64 s[4:5], s[34:35], 12
	v_lshl_add_u64 v[172:173], v[220:221], 0, s[4:5]
	s_nop 1
	v_readfirstlane_b32 s100, v172
	v_readfirstlane_b32 s101, v173
	s_nop 1
	v_subrev_u32_e32 v224, s100, v172
	s_nop 4
	global_load_dwordx2 v[130:131], v224, s[100:101]
	s_add_u32 s100, s100, 0x400000
	s_addc_u32 s101, s101, 0
	global_load_dwordx2 v[132:133], v224, s[100:101]
	s_add_u32 s100, s100, 0x400000
	s_addc_u32 s101, s101, 0
	global_load_dwordx2 v[134:135], v224, s[100:101]
	s_add_u32 s100, s100, 0x400000
	s_addc_u32 s101, s101, 0
	global_load_dwordx2 v[136:137], v224, s[100:101]
	s_add_u32 s100, s100, 0x400000
	s_addc_u32 s101, s101, 0
	global_load_dwordx2 v[138:139], v224, s[100:101]
	s_add_u32 s100, s100, 0x400000
	s_addc_u32 s101, s101, 0
	global_load_dwordx2 v[140:141], v224, s[100:101]
	s_add_u32 s100, s100, 0x400000
	s_addc_u32 s101, s101, 0
	global_load_dwordx2 v[142:143], v224, s[100:101]
	s_add_u32 s100, s100, 0x400000
	s_addc_u32 s101, s101, 0
	global_load_dwordx2 v[144:145], v224, s[100:101]
	s_sub_u32 s100, s100, 0x1c00000
	s_subb_u32 s101, s101, 0
	global_load_dwordx2 v[146:147], v224, s[100:101] offset:512
	s_add_u32 s100, s100, 0x400000
	s_addc_u32 s101, s101, 0
	global_load_dwordx2 v[148:149], v224, s[100:101] offset:512
	s_add_u32 s100, s100, 0x400000
	s_addc_u32 s101, s101, 0
	global_load_dwordx2 v[150:151], v224, s[100:101] offset:512
	s_add_u32 s100, s100, 0x400000
	s_addc_u32 s101, s101, 0
	global_load_dwordx2 v[152:153], v224, s[100:101] offset:512
	s_add_u32 s100, s100, 0x400000
	s_addc_u32 s101, s101, 0
	global_load_dwordx2 v[154:155], v224, s[100:101] offset:512
	s_add_u32 s100, s100, 0x400000
	s_addc_u32 s101, s101, 0
	global_load_dwordx2 v[156:157], v224, s[100:101] offset:512
	s_add_u32 s100, s100, 0x400000
	s_addc_u32 s101, s101, 0
	global_load_dwordx2 v[158:159], v224, s[100:101] offset:512
	s_add_u32 s100, s100, 0x400000
	s_addc_u32 s101, s101, 0
	global_load_dwordx2 v[160:161], v224, s[100:101] offset:512
	s_sub_u32 s100, s100, 0x1c00000
	s_subb_u32 s101, s101, 0
	global_load_dwordx2 v[162:163], v224, s[100:101] offset:1024
	s_add_u32 s100, s100, 0x400000
	s_addc_u32 s101, s101, 0
	global_load_dwordx2 v[164:165], v224, s[100:101] offset:1024
	s_add_u32 s100, s100, 0x400000
	s_addc_u32 s101, s101, 0
	global_load_dwordx2 v[166:167], v224, s[100:101] offset:1024
	s_add_u32 s100, s100, 0x400000
	s_addc_u32 s101, s101, 0
	global_load_dwordx2 v[168:169], v224, s[100:101] offset:1024
	s_add_u32 s100, s100, 0x400000
	s_addc_u32 s101, s101, 0
	global_load_dwordx2 v[170:171], v224, s[100:101] offset:1024
	s_add_u32 s100, s100, 0x400000
	s_addc_u32 s101, s101, 0
	global_load_dwordx2 v[172:173], v224, s[100:101] offset:1024
	s_add_u32 s100, s100, 0x400000
	s_addc_u32 s101, s101, 0
	global_load_dwordx2 v[174:175], v224, s[100:101] offset:1024
	s_add_u32 s100, s100, 0x400000
	s_addc_u32 s101, s101, 0
	global_load_dwordx2 v[176:177], v224, s[100:101] offset:1024
	s_sub_u32 s100, s100, 0x1c00000
	s_subb_u32 s101, s101, 0
	global_load_dwordx2 v[178:179], v224, s[100:101] offset:1536
	s_add_u32 s100, s100, 0x400000
	s_addc_u32 s101, s101, 0
	global_load_dwordx2 v[180:181], v224, s[100:101] offset:1536
	s_add_u32 s100, s100, 0x400000
	s_addc_u32 s101, s101, 0
	global_load_dwordx2 v[182:183], v224, s[100:101] offset:1536
	s_add_u32 s100, s100, 0x400000
	s_addc_u32 s101, s101, 0
	global_load_dwordx2 v[184:185], v224, s[100:101] offset:1536
	s_add_u32 s100, s100, 0x400000
	s_addc_u32 s101, s101, 0
	global_load_dwordx2 v[186:187], v224, s[100:101] offset:1536
	s_add_u32 s100, s100, 0x400000
	s_addc_u32 s101, s101, 0
	global_load_dwordx2 v[188:189], v224, s[100:101] offset:1536
	s_add_u32 s100, s100, 0x400000
	s_addc_u32 s101, s101, 0
	global_load_dwordx2 v[190:191], v224, s[100:101] offset:1536
	s_add_u32 s100, s100, 0x400000
	s_addc_u32 s101, s101, 0
	global_load_dwordx2 v[192:193], v224, s[100:101] offset:1536
	s_sub_u32 s100, s100, 0x1c00000
	s_subb_u32 s101, s101, 0
	s_waitcnt vmcnt(24)
	v_lshlrev_b32_e32 v232, 16, v130
	v_and_b32_e32 v233, 0xffff0000, v130
	v_lshlrev_b32_e32 v240, 16, v131
	v_and_b32_e32 v241, 0xffff0000, v131
	v_add_f32_e32 v232, 0, v232
	v_add_f32_e32 v233, 0, v233
	v_add_f32_e32 v240, 0, v240
	v_add_f32_e32 v241, 0, v241
	v_lshlrev_b32_e32 v225, 16, v132
	v_and_b32_e32 v132, 0xffff0000, v132
	v_add_f32_e32 v232, v232, v225
	v_add_f32_e32 v233, v233, v132
	v_lshlrev_b32_e32 v225, 16, v133
	v_and_b32_e32 v133, 0xffff0000, v133
	v_add_f32_e32 v240, v240, v225
	v_add_f32_e32 v241, v241, v133
	v_lshlrev_b32_e32 v225, 16, v134
	v_and_b32_e32 v134, 0xffff0000, v134
	v_add_f32_e32 v232, v232, v225
	v_add_f32_e32 v233, v233, v134
	v_lshlrev_b32_e32 v225, 16, v135
	v_and_b32_e32 v135, 0xffff0000, v135
	v_add_f32_e32 v240, v240, v225
	v_add_f32_e32 v241, v241, v135
	v_lshlrev_b32_e32 v225, 16, v136
	v_and_b32_e32 v136, 0xffff0000, v136
	v_add_f32_e32 v232, v232, v225
	v_add_f32_e32 v233, v233, v136
	v_lshlrev_b32_e32 v225, 16, v137
	v_and_b32_e32 v137, 0xffff0000, v137
	v_add_f32_e32 v240, v240, v225
	v_add_f32_e32 v241, v241, v137
	v_lshlrev_b32_e32 v225, 16, v138
	v_and_b32_e32 v138, 0xffff0000, v138
	v_add_f32_e32 v232, v232, v225
	v_add_f32_e32 v233, v233, v138
	v_lshlrev_b32_e32 v225, 16, v139
	v_and_b32_e32 v139, 0xffff0000, v139
	v_add_f32_e32 v240, v240, v225
	v_add_f32_e32 v241, v241, v139
	v_lshlrev_b32_e32 v225, 16, v140
	v_and_b32_e32 v140, 0xffff0000, v140
	v_add_f32_e32 v232, v232, v225
	v_add_f32_e32 v233, v233, v140
	v_lshlrev_b32_e32 v225, 16, v141
	v_and_b32_e32 v141, 0xffff0000, v141
	v_add_f32_e32 v240, v240, v225
	v_add_f32_e32 v241, v241, v141
	v_lshlrev_b32_e32 v225, 16, v142
	v_and_b32_e32 v142, 0xffff0000, v142
	v_add_f32_e32 v232, v232, v225
	v_add_f32_e32 v233, v233, v142
	v_lshlrev_b32_e32 v225, 16, v143
	v_and_b32_e32 v143, 0xffff0000, v143
	v_add_f32_e32 v240, v240, v225
	v_add_f32_e32 v241, v241, v143
	v_lshlrev_b32_e32 v225, 16, v144
	v_and_b32_e32 v144, 0xffff0000, v144
	v_add_f32_e32 v232, v232, v225
	v_add_f32_e32 v233, v233, v144
	v_lshlrev_b32_e32 v225, 16, v145
	v_and_b32_e32 v145, 0xffff0000, v145
	v_add_f32_e32 v240, v240, v225
	v_add_f32_e32 v241, v241, v145
	v_mov_b32_e32 v130, v232
	v_mov_b32_e32 v131, v233
	v_mov_b32_e32 v132, v240
	v_mov_b32_e32 v133, v241
	s_waitcnt vmcnt(16)
	v_lshlrev_b32_e32 v134, 16, v146
	v_and_b32_e32 v135, 0xffff0000, v146
	v_lshlrev_b32_e32 v136, 16, v147
	v_and_b32_e32 v137, 0xffff0000, v147
	v_add_f32_e32 v134, 0, v134
	v_add_f32_e32 v135, 0, v135
	v_add_f32_e32 v136, 0, v136
	v_add_f32_e32 v137, 0, v137
	v_lshlrev_b32_e32 v225, 16, v148
	v_and_b32_e32 v148, 0xffff0000, v148
	v_add_f32_e32 v134, v134, v225
	v_add_f32_e32 v135, v135, v148
	v_lshlrev_b32_e32 v225, 16, v149
	v_and_b32_e32 v149, 0xffff0000, v149
	v_add_f32_e32 v136, v136, v225
	v_add_f32_e32 v137, v137, v149
	v_lshlrev_b32_e32 v225, 16, v150
	v_and_b32_e32 v150, 0xffff0000, v150
	v_add_f32_e32 v134, v134, v225
	v_add_f32_e32 v135, v135, v150
	v_lshlrev_b32_e32 v225, 16, v151
	v_and_b32_e32 v151, 0xffff0000, v151
	v_add_f32_e32 v136, v136, v225
	v_add_f32_e32 v137, v137, v151
	v_lshlrev_b32_e32 v225, 16, v152
	v_and_b32_e32 v152, 0xffff0000, v152
	v_add_f32_e32 v134, v134, v225
	v_add_f32_e32 v135, v135, v152
	v_lshlrev_b32_e32 v225, 16, v153
	v_and_b32_e32 v153, 0xffff0000, v153
	v_add_f32_e32 v136, v136, v225
	v_add_f32_e32 v137, v137, v153
	v_lshlrev_b32_e32 v225, 16, v154
	v_and_b32_e32 v154, 0xffff0000, v154
	v_add_f32_e32 v134, v134, v225
	v_add_f32_e32 v135, v135, v154
	v_lshlrev_b32_e32 v225, 16, v155
	v_and_b32_e32 v155, 0xffff0000, v155
	v_add_f32_e32 v136, v136, v225
	v_add_f32_e32 v137, v137, v155
	v_lshlrev_b32_e32 v225, 16, v156
	v_and_b32_e32 v156, 0xffff0000, v156
	v_add_f32_e32 v134, v134, v225
	v_add_f32_e32 v135, v135, v156
	v_lshlrev_b32_e32 v225, 16, v157
	v_and_b32_e32 v157, 0xffff0000, v157
	v_add_f32_e32 v136, v136, v225
	v_add_f32_e32 v137, v137, v157
	v_lshlrev_b32_e32 v225, 16, v158
	v_and_b32_e32 v158, 0xffff0000, v158
	v_add_f32_e32 v134, v134, v225
	v_add_f32_e32 v135, v135, v158
	v_lshlrev_b32_e32 v225, 16, v159
	v_and_b32_e32 v159, 0xffff0000, v159
	v_add_f32_e32 v136, v136, v225
	v_add_f32_e32 v137, v137, v159
	v_lshlrev_b32_e32 v225, 16, v160
	v_and_b32_e32 v160, 0xffff0000, v160
	v_add_f32_e32 v134, v134, v225
	v_add_f32_e32 v135, v135, v160
	v_lshlrev_b32_e32 v225, 16, v161
	v_and_b32_e32 v161, 0xffff0000, v161
	v_add_f32_e32 v136, v136, v225
	v_add_f32_e32 v137, v137, v161
	global_load_dwordx2 v[146:147], v224, s[100:101] offset:2048
	s_add_u32 s100, s100, 0x400000
	s_addc_u32 s101, s101, 0
	global_load_dwordx2 v[148:149], v224, s[100:101] offset:2048
	s_add_u32 s100, s100, 0x400000
	s_addc_u32 s101, s101, 0
	global_load_dwordx2 v[150:151], v224, s[100:101] offset:2048
	s_add_u32 s100, s100, 0x400000
	s_addc_u32 s101, s101, 0
	global_load_dwordx2 v[152:153], v224, s[100:101] offset:2048
	s_add_u32 s100, s100, 0x400000
	s_addc_u32 s101, s101, 0
	global_load_dwordx2 v[154:155], v224, s[100:101] offset:2048
	s_add_u32 s100, s100, 0x400000
	s_addc_u32 s101, s101, 0
	global_load_dwordx2 v[156:157], v224, s[100:101] offset:2048
	s_add_u32 s100, s100, 0x400000
	s_addc_u32 s101, s101, 0
	global_load_dwordx2 v[158:159], v224, s[100:101] offset:2048
	s_add_u32 s100, s100, 0x400000
	s_addc_u32 s101, s101, 0
	global_load_dwordx2 v[160:161], v224, s[100:101] offset:2048
	s_sub_u32 s100, s100, 0x1c00000
	s_subb_u32 s101, s101, 0
	s_waitcnt vmcnt(16)
	v_lshlrev_b32_e32 v138, 16, v162
	v_and_b32_e32 v139, 0xffff0000, v162
	v_lshlrev_b32_e32 v140, 16, v163
	v_and_b32_e32 v141, 0xffff0000, v163
	v_add_f32_e32 v138, 0, v138
	v_add_f32_e32 v139, 0, v139
	v_add_f32_e32 v140, 0, v140
	v_add_f32_e32 v141, 0, v141
	v_lshlrev_b32_e32 v225, 16, v164
	v_and_b32_e32 v164, 0xffff0000, v164
	v_add_f32_e32 v138, v138, v225
	v_add_f32_e32 v139, v139, v164
	v_lshlrev_b32_e32 v225, 16, v165
	v_and_b32_e32 v165, 0xffff0000, v165
	v_add_f32_e32 v140, v140, v225
	v_add_f32_e32 v141, v141, v165
	v_lshlrev_b32_e32 v225, 16, v166
	v_and_b32_e32 v166, 0xffff0000, v166
	v_add_f32_e32 v138, v138, v225
	v_add_f32_e32 v139, v139, v166
	v_lshlrev_b32_e32 v225, 16, v167
	v_and_b32_e32 v167, 0xffff0000, v167
	v_add_f32_e32 v140, v140, v225
	v_add_f32_e32 v141, v141, v167
	v_lshlrev_b32_e32 v225, 16, v168
	v_and_b32_e32 v168, 0xffff0000, v168
	v_add_f32_e32 v138, v138, v225
	v_add_f32_e32 v139, v139, v168
	v_lshlrev_b32_e32 v225, 16, v169
	v_and_b32_e32 v169, 0xffff0000, v169
	v_add_f32_e32 v140, v140, v225
	v_add_f32_e32 v141, v141, v169
	v_lshlrev_b32_e32 v225, 16, v170
	v_and_b32_e32 v170, 0xffff0000, v170
	v_add_f32_e32 v138, v138, v225
	v_add_f32_e32 v139, v139, v170
	v_lshlrev_b32_e32 v225, 16, v171
	v_and_b32_e32 v171, 0xffff0000, v171
	v_add_f32_e32 v140, v140, v225
	v_add_f32_e32 v141, v141, v171
	v_lshlrev_b32_e32 v225, 16, v172
	v_and_b32_e32 v172, 0xffff0000, v172
	v_add_f32_e32 v138, v138, v225
	v_add_f32_e32 v139, v139, v172
	v_lshlrev_b32_e32 v225, 16, v173
	v_and_b32_e32 v173, 0xffff0000, v173
	v_add_f32_e32 v140, v140, v225
	v_add_f32_e32 v141, v141, v173
	v_lshlrev_b32_e32 v225, 16, v174
	v_and_b32_e32 v174, 0xffff0000, v174
	v_add_f32_e32 v138, v138, v225
	v_add_f32_e32 v139, v139, v174
	v_lshlrev_b32_e32 v225, 16, v175
	v_and_b32_e32 v175, 0xffff0000, v175
	v_add_f32_e32 v140, v140, v225
	v_add_f32_e32 v141, v141, v175
	v_lshlrev_b32_e32 v225, 16, v176
	v_and_b32_e32 v176, 0xffff0000, v176
	v_add_f32_e32 v138, v138, v225
	v_add_f32_e32 v139, v139, v176
	v_lshlrev_b32_e32 v225, 16, v177
	v_and_b32_e32 v177, 0xffff0000, v177
	v_add_f32_e32 v140, v140, v225
	v_add_f32_e32 v141, v141, v177
	global_load_dwordx2 v[162:163], v224, s[100:101] offset:2560
	s_add_u32 s100, s100, 0x400000
	s_addc_u32 s101, s101, 0
	global_load_dwordx2 v[164:165], v224, s[100:101] offset:2560
	s_add_u32 s100, s100, 0x400000
	s_addc_u32 s101, s101, 0
	global_load_dwordx2 v[166:167], v224, s[100:101] offset:2560
	s_add_u32 s100, s100, 0x400000
	s_addc_u32 s101, s101, 0
	global_load_dwordx2 v[168:169], v224, s[100:101] offset:2560
	s_add_u32 s100, s100, 0x400000
	s_addc_u32 s101, s101, 0
	global_load_dwordx2 v[170:171], v224, s[100:101] offset:2560
	s_add_u32 s100, s100, 0x400000
	s_addc_u32 s101, s101, 0
	global_load_dwordx2 v[172:173], v224, s[100:101] offset:2560
	s_add_u32 s100, s100, 0x400000
	s_addc_u32 s101, s101, 0
	global_load_dwordx2 v[174:175], v224, s[100:101] offset:2560
	s_add_u32 s100, s100, 0x400000
	s_addc_u32 s101, s101, 0
	global_load_dwordx2 v[176:177], v224, s[100:101] offset:2560
	s_sub_u32 s100, s100, 0x1c00000
	s_subb_u32 s101, s101, 0
	s_waitcnt vmcnt(16)
	v_lshlrev_b32_e32 v142, 16, v178
	v_and_b32_e32 v143, 0xffff0000, v178
	v_lshlrev_b32_e32 v144, 16, v179
	v_and_b32_e32 v145, 0xffff0000, v179
	v_add_f32_e32 v142, 0, v142
	v_add_f32_e32 v143, 0, v143
	v_add_f32_e32 v144, 0, v144
	v_add_f32_e32 v145, 0, v145
	v_lshlrev_b32_e32 v225, 16, v180
	v_and_b32_e32 v180, 0xffff0000, v180
	v_add_f32_e32 v142, v142, v225
	v_add_f32_e32 v143, v143, v180
	v_lshlrev_b32_e32 v225, 16, v181
	v_and_b32_e32 v181, 0xffff0000, v181
	v_add_f32_e32 v144, v144, v225
	v_add_f32_e32 v145, v145, v181
	v_lshlrev_b32_e32 v225, 16, v182
	v_and_b32_e32 v182, 0xffff0000, v182
	v_add_f32_e32 v142, v142, v225
	v_add_f32_e32 v143, v143, v182
	v_lshlrev_b32_e32 v225, 16, v183
	v_and_b32_e32 v183, 0xffff0000, v183
	v_add_f32_e32 v144, v144, v225
	v_add_f32_e32 v145, v145, v183
	v_lshlrev_b32_e32 v225, 16, v184
	v_and_b32_e32 v184, 0xffff0000, v184
	v_add_f32_e32 v142, v142, v225
	v_add_f32_e32 v143, v143, v184
	v_lshlrev_b32_e32 v225, 16, v185
	v_and_b32_e32 v185, 0xffff0000, v185
	v_add_f32_e32 v144, v144, v225
	v_add_f32_e32 v145, v145, v185
	v_lshlrev_b32_e32 v225, 16, v186
	v_and_b32_e32 v186, 0xffff0000, v186
	v_add_f32_e32 v142, v142, v225
	v_add_f32_e32 v143, v143, v186
	v_lshlrev_b32_e32 v225, 16, v187
	v_and_b32_e32 v187, 0xffff0000, v187
	v_add_f32_e32 v144, v144, v225
	v_add_f32_e32 v145, v145, v187
	v_lshlrev_b32_e32 v225, 16, v188
	v_and_b32_e32 v188, 0xffff0000, v188
	v_add_f32_e32 v142, v142, v225
	v_add_f32_e32 v143, v143, v188
	v_lshlrev_b32_e32 v225, 16, v189
	v_and_b32_e32 v189, 0xffff0000, v189
	v_add_f32_e32 v144, v144, v225
	v_add_f32_e32 v145, v145, v189
	v_lshlrev_b32_e32 v225, 16, v190
	v_and_b32_e32 v190, 0xffff0000, v190
	v_add_f32_e32 v142, v142, v225
	v_add_f32_e32 v143, v143, v190
	v_lshlrev_b32_e32 v225, 16, v191
	v_and_b32_e32 v191, 0xffff0000, v191
	v_add_f32_e32 v144, v144, v225
	v_add_f32_e32 v145, v145, v191
	v_lshlrev_b32_e32 v225, 16, v192
	v_and_b32_e32 v192, 0xffff0000, v192
	v_add_f32_e32 v142, v142, v225
	v_add_f32_e32 v143, v143, v192
	v_lshlrev_b32_e32 v225, 16, v193
	v_and_b32_e32 v193, 0xffff0000, v193
	v_add_f32_e32 v144, v144, v225
	v_add_f32_e32 v145, v145, v193
	global_load_dwordx2 v[178:179], v224, s[100:101] offset:3072
	s_add_u32 s100, s100, 0x400000
	s_addc_u32 s101, s101, 0
	global_load_dwordx2 v[180:181], v224, s[100:101] offset:3072
	s_add_u32 s100, s100, 0x400000
	s_addc_u32 s101, s101, 0
	global_load_dwordx2 v[182:183], v224, s[100:101] offset:3072
	s_add_u32 s100, s100, 0x400000
	s_addc_u32 s101, s101, 0
	global_load_dwordx2 v[184:185], v224, s[100:101] offset:3072
	s_add_u32 s100, s100, 0x400000
	s_addc_u32 s101, s101, 0
	global_load_dwordx2 v[186:187], v224, s[100:101] offset:3072
	s_add_u32 s100, s100, 0x400000
	s_addc_u32 s101, s101, 0
	global_load_dwordx2 v[188:189], v224, s[100:101] offset:3072
	s_add_u32 s100, s100, 0x400000
	s_addc_u32 s101, s101, 0
	global_load_dwordx2 v[190:191], v224, s[100:101] offset:3072
	s_add_u32 s100, s100, 0x400000
	s_addc_u32 s101, s101, 0
	global_load_dwordx2 v[192:193], v224, s[100:101] offset:3072
	s_sub_u32 s100, s100, 0x1c00000
	s_subb_u32 s101, s101, 0
	s_waitcnt vmcnt(16)
	v_lshlrev_b32_e32 v232, 16, v146
	v_and_b32_e32 v233, 0xffff0000, v146
	v_lshlrev_b32_e32 v240, 16, v147
	v_and_b32_e32 v241, 0xffff0000, v147
	v_add_f32_e32 v232, 0, v232
	v_add_f32_e32 v233, 0, v233
	v_add_f32_e32 v240, 0, v240
	v_add_f32_e32 v241, 0, v241
	v_lshlrev_b32_e32 v225, 16, v148
	v_and_b32_e32 v148, 0xffff0000, v148
	v_add_f32_e32 v232, v232, v225
	v_add_f32_e32 v233, v233, v148
	v_lshlrev_b32_e32 v225, 16, v149
	v_and_b32_e32 v149, 0xffff0000, v149
	v_add_f32_e32 v240, v240, v225
	v_add_f32_e32 v241, v241, v149
	v_lshlrev_b32_e32 v225, 16, v150
	v_and_b32_e32 v150, 0xffff0000, v150
	v_add_f32_e32 v232, v232, v225
	v_add_f32_e32 v233, v233, v150
	v_lshlrev_b32_e32 v225, 16, v151
	v_and_b32_e32 v151, 0xffff0000, v151
	v_add_f32_e32 v240, v240, v225
	v_add_f32_e32 v241, v241, v151
	v_lshlrev_b32_e32 v225, 16, v152
	v_and_b32_e32 v152, 0xffff0000, v152
	v_add_f32_e32 v232, v232, v225
	v_add_f32_e32 v233, v233, v152
	v_lshlrev_b32_e32 v225, 16, v153
	v_and_b32_e32 v153, 0xffff0000, v153
	v_add_f32_e32 v240, v240, v225
	v_add_f32_e32 v241, v241, v153
	v_lshlrev_b32_e32 v225, 16, v154
	v_and_b32_e32 v154, 0xffff0000, v154
	v_add_f32_e32 v232, v232, v225
	v_add_f32_e32 v233, v233, v154
	v_lshlrev_b32_e32 v225, 16, v155
	v_and_b32_e32 v155, 0xffff0000, v155
	v_add_f32_e32 v240, v240, v225
	v_add_f32_e32 v241, v241, v155
	v_lshlrev_b32_e32 v225, 16, v156
	v_and_b32_e32 v156, 0xffff0000, v156
	v_add_f32_e32 v232, v232, v225
	v_add_f32_e32 v233, v233, v156
	v_lshlrev_b32_e32 v225, 16, v157
	v_and_b32_e32 v157, 0xffff0000, v157
	v_add_f32_e32 v240, v240, v225
	v_add_f32_e32 v241, v241, v157
	v_lshlrev_b32_e32 v225, 16, v158
	v_and_b32_e32 v158, 0xffff0000, v158
	v_add_f32_e32 v232, v232, v225
	v_add_f32_e32 v233, v233, v158
	v_lshlrev_b32_e32 v225, 16, v159
	v_and_b32_e32 v159, 0xffff0000, v159
	v_add_f32_e32 v240, v240, v225
	v_add_f32_e32 v241, v241, v159
	v_lshlrev_b32_e32 v225, 16, v160
	v_and_b32_e32 v160, 0xffff0000, v160
	v_add_f32_e32 v232, v232, v225
	v_add_f32_e32 v233, v233, v160
	v_lshlrev_b32_e32 v225, 16, v161
	v_and_b32_e32 v161, 0xffff0000, v161
	v_add_f32_e32 v240, v240, v225
	v_add_f32_e32 v241, v241, v161
	v_mov_b32_e32 v146, v232
	v_mov_b32_e32 v147, v233
	v_mov_b32_e32 v148, v240
	v_mov_b32_e32 v149, v241
	s_waitcnt vmcnt(8)
	v_lshlrev_b32_e32 v150, 16, v162
	v_and_b32_e32 v151, 0xffff0000, v162
	v_lshlrev_b32_e32 v152, 16, v163
	v_and_b32_e32 v153, 0xffff0000, v163
	v_add_f32_e32 v150, 0, v150
	v_add_f32_e32 v151, 0, v151
	v_add_f32_e32 v152, 0, v152
	v_add_f32_e32 v153, 0, v153
	v_lshlrev_b32_e32 v225, 16, v164
	v_and_b32_e32 v164, 0xffff0000, v164
	v_add_f32_e32 v150, v150, v225
	v_add_f32_e32 v151, v151, v164
	v_lshlrev_b32_e32 v225, 16, v165
	v_and_b32_e32 v165, 0xffff0000, v165
	v_add_f32_e32 v152, v152, v225
	v_add_f32_e32 v153, v153, v165
	v_lshlrev_b32_e32 v225, 16, v166
	v_and_b32_e32 v166, 0xffff0000, v166
	v_add_f32_e32 v150, v150, v225
	v_add_f32_e32 v151, v151, v166
	v_lshlrev_b32_e32 v225, 16, v167
	v_and_b32_e32 v167, 0xffff0000, v167
	v_add_f32_e32 v152, v152, v225
	v_add_f32_e32 v153, v153, v167
	v_lshlrev_b32_e32 v225, 16, v168
	v_and_b32_e32 v168, 0xffff0000, v168
	v_add_f32_e32 v150, v150, v225
	v_add_f32_e32 v151, v151, v168
	v_lshlrev_b32_e32 v225, 16, v169
	v_and_b32_e32 v169, 0xffff0000, v169
	v_add_f32_e32 v152, v152, v225
	v_add_f32_e32 v153, v153, v169
	v_lshlrev_b32_e32 v225, 16, v170
	v_and_b32_e32 v170, 0xffff0000, v170
	v_add_f32_e32 v150, v150, v225
	v_add_f32_e32 v151, v151, v170
	v_lshlrev_b32_e32 v225, 16, v171
	v_and_b32_e32 v171, 0xffff0000, v171
	v_add_f32_e32 v152, v152, v225
	v_add_f32_e32 v153, v153, v171
	v_lshlrev_b32_e32 v225, 16, v172
	v_and_b32_e32 v172, 0xffff0000, v172
	v_add_f32_e32 v150, v150, v225
	v_add_f32_e32 v151, v151, v172
	v_lshlrev_b32_e32 v225, 16, v173
	v_and_b32_e32 v173, 0xffff0000, v173
	v_add_f32_e32 v152, v152, v225
	v_add_f32_e32 v153, v153, v173
	v_lshlrev_b32_e32 v225, 16, v174
	v_and_b32_e32 v174, 0xffff0000, v174
	v_add_f32_e32 v150, v150, v225
	v_add_f32_e32 v151, v151, v174
	v_lshlrev_b32_e32 v225, 16, v175
	v_and_b32_e32 v175, 0xffff0000, v175
	v_add_f32_e32 v152, v152, v225
	v_add_f32_e32 v153, v153, v175
	v_lshlrev_b32_e32 v225, 16, v176
	v_and_b32_e32 v176, 0xffff0000, v176
	v_add_f32_e32 v150, v150, v225
	v_add_f32_e32 v151, v151, v176
	v_lshlrev_b32_e32 v225, 16, v177
	v_and_b32_e32 v177, 0xffff0000, v177
	v_add_f32_e32 v152, v152, v225
	v_add_f32_e32 v153, v153, v177
	global_load_dwordx2 v[162:163], v224, s[100:101] offset:3584
	s_add_u32 s100, s100, 0x400000
	s_addc_u32 s101, s101, 0
	global_load_dwordx2 v[164:165], v224, s[100:101] offset:3584
	s_add_u32 s100, s100, 0x400000
	s_addc_u32 s101, s101, 0
	global_load_dwordx2 v[166:167], v224, s[100:101] offset:3584
	s_add_u32 s100, s100, 0x400000
	s_addc_u32 s101, s101, 0
	global_load_dwordx2 v[168:169], v224, s[100:101] offset:3584
	s_add_u32 s100, s100, 0x400000
	s_addc_u32 s101, s101, 0
	global_load_dwordx2 v[170:171], v224, s[100:101] offset:3584
	s_add_u32 s100, s100, 0x400000
	s_addc_u32 s101, s101, 0
	global_load_dwordx2 v[172:173], v224, s[100:101] offset:3584
	s_add_u32 s100, s100, 0x400000
	s_addc_u32 s101, s101, 0
	global_load_dwordx2 v[174:175], v224, s[100:101] offset:3584
	s_add_u32 s100, s100, 0x400000
	s_addc_u32 s101, s101, 0
	global_load_dwordx2 v[176:177], v224, s[100:101] offset:3584
	s_sub_u32 s100, s100, 0x1c00000
	s_subb_u32 s101, s101, 0
	s_waitcnt vmcnt(8)
	v_lshlrev_b32_e32 v154, 16, v178
	v_and_b32_e32 v155, 0xffff0000, v178
	v_lshlrev_b32_e32 v156, 16, v179
	v_and_b32_e32 v157, 0xffff0000, v179
	v_add_f32_e32 v154, 0, v154
	v_add_f32_e32 v155, 0, v155
	v_add_f32_e32 v156, 0, v156
	v_add_f32_e32 v157, 0, v157
	v_lshlrev_b32_e32 v225, 16, v180
	v_and_b32_e32 v180, 0xffff0000, v180
	v_add_f32_e32 v154, v154, v225
	v_add_f32_e32 v155, v155, v180
	v_lshlrev_b32_e32 v225, 16, v181
	v_and_b32_e32 v181, 0xffff0000, v181
	v_add_f32_e32 v156, v156, v225
	v_add_f32_e32 v157, v157, v181
	v_lshlrev_b32_e32 v225, 16, v182
	v_and_b32_e32 v182, 0xffff0000, v182
	v_add_f32_e32 v154, v154, v225
	v_add_f32_e32 v155, v155, v182
	v_lshlrev_b32_e32 v225, 16, v183
	v_and_b32_e32 v183, 0xffff0000, v183
	v_add_f32_e32 v156, v156, v225
	v_add_f32_e32 v157, v157, v183
	v_lshlrev_b32_e32 v225, 16, v184
	v_and_b32_e32 v184, 0xffff0000, v184
	v_add_f32_e32 v154, v154, v225
	v_add_f32_e32 v155, v155, v184
	v_lshlrev_b32_e32 v225, 16, v185
	v_and_b32_e32 v185, 0xffff0000, v185
	v_add_f32_e32 v156, v156, v225
	v_add_f32_e32 v157, v157, v185
	v_lshlrev_b32_e32 v225, 16, v186
	v_and_b32_e32 v186, 0xffff0000, v186
	v_add_f32_e32 v154, v154, v225
	v_add_f32_e32 v155, v155, v186
	v_lshlrev_b32_e32 v225, 16, v187
	v_and_b32_e32 v187, 0xffff0000, v187
	v_add_f32_e32 v156, v156, v225
	v_add_f32_e32 v157, v157, v187
	v_lshlrev_b32_e32 v225, 16, v188
	v_and_b32_e32 v188, 0xffff0000, v188
	v_add_f32_e32 v154, v154, v225
	v_add_f32_e32 v155, v155, v188
	v_lshlrev_b32_e32 v225, 16, v189
	v_and_b32_e32 v189, 0xffff0000, v189
	v_add_f32_e32 v156, v156, v225
	v_add_f32_e32 v157, v157, v189
	v_lshlrev_b32_e32 v225, 16, v190
	v_and_b32_e32 v190, 0xffff0000, v190
	v_add_f32_e32 v154, v154, v225
	v_add_f32_e32 v155, v155, v190
	v_lshlrev_b32_e32 v225, 16, v191
	v_and_b32_e32 v191, 0xffff0000, v191
	v_add_f32_e32 v156, v156, v225
	v_add_f32_e32 v157, v157, v191
	v_lshlrev_b32_e32 v225, 16, v192
	v_and_b32_e32 v192, 0xffff0000, v192
	v_add_f32_e32 v154, v154, v225
	v_add_f32_e32 v155, v155, v192
	v_lshlrev_b32_e32 v225, 16, v193
	v_and_b32_e32 v193, 0xffff0000, v193
	v_add_f32_e32 v156, v156, v225
	v_add_f32_e32 v157, v157, v193
	s_waitcnt vmcnt(0)
	v_lshlrev_b32_e32 v158, 16, v162
	v_and_b32_e32 v159, 0xffff0000, v162
	v_lshlrev_b32_e32 v160, 16, v163
	v_and_b32_e32 v161, 0xffff0000, v163
	v_add_f32_e32 v158, 0, v158
	v_add_f32_e32 v159, 0, v159
	v_add_f32_e32 v160, 0, v160
	v_add_f32_e32 v161, 0, v161
	v_lshlrev_b32_e32 v225, 16, v164
	v_and_b32_e32 v164, 0xffff0000, v164
	v_add_f32_e32 v158, v158, v225
	v_add_f32_e32 v159, v159, v164
	v_lshlrev_b32_e32 v225, 16, v165
	v_and_b32_e32 v165, 0xffff0000, v165
	v_add_f32_e32 v160, v160, v225
	v_add_f32_e32 v161, v161, v165
	v_lshlrev_b32_e32 v225, 16, v166
	v_and_b32_e32 v166, 0xffff0000, v166
	v_add_f32_e32 v158, v158, v225
	v_add_f32_e32 v159, v159, v166
	v_lshlrev_b32_e32 v225, 16, v167
	v_and_b32_e32 v167, 0xffff0000, v167
	v_add_f32_e32 v160, v160, v225
	v_add_f32_e32 v161, v161, v167
	v_lshlrev_b32_e32 v225, 16, v168
	v_and_b32_e32 v168, 0xffff0000, v168
	v_add_f32_e32 v158, v158, v225
	v_add_f32_e32 v159, v159, v168
	v_lshlrev_b32_e32 v225, 16, v169
	v_and_b32_e32 v169, 0xffff0000, v169
	v_add_f32_e32 v160, v160, v225
	v_add_f32_e32 v161, v161, v169
	v_lshlrev_b32_e32 v225, 16, v170
	v_and_b32_e32 v170, 0xffff0000, v170
	v_add_f32_e32 v158, v158, v225
	v_add_f32_e32 v159, v159, v170
	v_lshlrev_b32_e32 v225, 16, v171
	v_and_b32_e32 v171, 0xffff0000, v171
	v_add_f32_e32 v160, v160, v225
	v_add_f32_e32 v161, v161, v171
	v_lshlrev_b32_e32 v225, 16, v172
	v_and_b32_e32 v172, 0xffff0000, v172
	v_add_f32_e32 v158, v158, v225
	v_add_f32_e32 v159, v159, v172
	v_lshlrev_b32_e32 v225, 16, v173
	v_and_b32_e32 v173, 0xffff0000, v173
	v_add_f32_e32 v160, v160, v225
	v_add_f32_e32 v161, v161, v173
	v_lshlrev_b32_e32 v225, 16, v174
	v_and_b32_e32 v174, 0xffff0000, v174
	v_add_f32_e32 v158, v158, v225
	v_add_f32_e32 v159, v159, v174
	v_lshlrev_b32_e32 v225, 16, v175
	v_and_b32_e32 v175, 0xffff0000, v175
	v_add_f32_e32 v160, v160, v225
	v_add_f32_e32 v161, v161, v175
	v_lshlrev_b32_e32 v225, 16, v176
	v_and_b32_e32 v176, 0xffff0000, v176
	v_add_f32_e32 v158, v158, v225
	v_add_f32_e32 v159, v159, v176
	v_lshlrev_b32_e32 v225, 16, v177
	v_and_b32_e32 v177, 0xffff0000, v177
	v_add_f32_e32 v160, v160, v225
	v_add_f32_e32 v161, v161, v177

	.amdhsa_kernel _Z3fwd4Args
		.amdhsa_group_segment_fixed_size 0
		.amdhsa_private_segment_fixed_size 0
		.amdhsa_kernarg_size 568
		.amdhsa_user_sgpr_count 2
		.amdhsa_user_sgpr_dispatch_ptr 0
		.amdhsa_user_sgpr_queue_ptr 0
		.amdhsa_user_sgpr_kernarg_segment_ptr 1
		.amdhsa_user_sgpr_dispatch_id 0
		.amdhsa_user_sgpr_kernarg_preload_length 0
		.amdhsa_user_sgpr_kernarg_preload_offset 0
		.amdhsa_user_sgpr_private_segment_size 0
		.amdhsa_uses_dynamic_stack 0
		.amdhsa_enable_private_segment 0
		.amdhsa_system_sgpr_workgroup_id_x 1
		.amdhsa_system_sgpr_workgroup_id_y 0
		.amdhsa_system_sgpr_workgroup_id_z 0
		.amdhsa_system_sgpr_workgroup_info 0
		.amdhsa_system_vgpr_workitem_id 0
		.amdhsa_next_free_vgpr 256
		.amdhsa_next_free_sgpr 102
		.amdhsa_accum_offset 256
		.amdhsa_reserve_vcc 1
		.amdhsa_float_round_mode_32 0
		.amdhsa_float_round_mode_16_64 0
		.amdhsa_float_denorm_mode_32 3
		.amdhsa_float_denorm_mode_16_64 3
		.amdhsa_dx10_clamp 1
		.amdhsa_ieee_mode 1
		.amdhsa_fp16_overflow 0
		.amdhsa_tg_split 0
		.amdhsa_exception_fp_ieee_invalid_op 0
		.amdhsa_exception_fp_denorm_src 0
		.amdhsa_exception_fp_ieee_div_zero 0
		.amdhsa_exception_fp_ieee_overflow 0
		.amdhsa_exception_fp_ieee_underflow 0
		.amdhsa_exception_fp_ieee_inexact 0
		.amdhsa_exception_int_div_zero 0
	.end_amdhsa_kernel

.Lfunc_end0:
	.size	_Z3fwd4Args, .Lfunc_end0-_Z3fwd4Args
	.set _Z3fwd4Args.num_vgpr, 256
	.set _Z3fwd4Args.num_agpr, 0
	.set _Z3fwd4Args.numbered_sgpr, 102
	.set _Z3fwd4Args.num_named_barrier, 0
	.set _Z3fwd4Args.private_seg_size, 0
	.set _Z3fwd4Args.uses_vcc, 1
	.set _Z3fwd4Args.uses_flat_scratch, 0
	.set _Z3fwd4Args.has_dyn_sized_stack, 0
	.set _Z3fwd4Args.has_recursion, 0
	.set _Z3fwd4Args.has_indirect_call, 0

amdhsa.kernels:
  - .agpr_count:     0
    .args:
      - .offset:         0
        .size:           312
        .value_kind:     by_value
      - .offset:         312
        .size:           4
        .value_kind:     hidden_block_count_x
      - .offset:         316
        .size:           4
        .value_kind:     hidden_block_count_y
      - .offset:         320
        .size:           4
        .value_kind:     hidden_block_count_z
      - .offset:         324
        .size:           2
        .value_kind:     hidden_group_size_x
      - .offset:         326
        .size:           2
        .value_kind:     hidden_group_size_y
      - .offset:         328
        .size:           2
        .value_kind:     hidden_group_size_z
      - .offset:         330
        .size:           2
        .value_kind:     hidden_remainder_x
      - .offset:         332
        .size:           2
        .value_kind:     hidden_remainder_y
      - .offset:         334
        .size:           2
        .value_kind:     hidden_remainder_z
      - .offset:         352
        .size:           8
        .value_kind:     hidden_global_offset_x
      - .offset:         360
        .size:           8
        .value_kind:     hidden_global_offset_y
      - .offset:         368
        .size:           8
        .value_kind:     hidden_global_offset_z
      - .offset:         376
        .size:           2
        .value_kind:     hidden_grid_dims
      - .offset:         432
        .size:           4
        .value_kind:     hidden_dynamic_lds_size
    .group_segment_fixed_size: 0
    .kernarg_segment_align: 8
    .kernarg_segment_size: 568
    .language:       OpenCL C
    .language_version:
      - 2
      - 0
    .max_flat_workgroup_size: 512
    .name:           _Z3fwd4Args
    .private_segment_fixed_size: 0
    .sgpr_count:     108
    .sgpr_spill_count: 158
    .symbol:         _Z3fwd4Args.kd
    .uniform_work_group_size: 1
    .uses_dynamic_stack: false
    .vgpr_count:     256
    .vgpr_spill_count: 0
    .wavefront_size: 64
